# nt (non-temporal) hint on the one-shot f32 weight loads of the conversion loops (on top of permlane/saddr/EpiVT-wait stack)
# speedup vs baseline: 1.0098x; 1.0098x over previous
.LBB0_8:
	s_and_b64 s[4:5], s[4:5], exec
	s_mul_i32 s16, s16, s14
	s_cselect_b32 s17, s29, s27
	s_cselect_b32 s18, s28, s26
	s_sub_i32 s4, s15, s16
	s_lshl_b32 s4, s4, 5
	s_ashr_i32 s5, s4, 31
	s_lshl_b64 s[4:5], s[4:5], 2
	v_and_b32_e32 v4, 31, v34
	s_add_u32 s4, s18, s4
	s_addc_u32 s5, s17, s5
	v_lshlrev_b32_e32 v4, 2, v4
	v_mov_b32_e32 v5, 0
	v_lshl_add_u64 v[4:5], s[4:5], 0, v[4:5]
	v_mad_i64_i32 v[8:9], s[4:5], v2, s9, 0
	v_lshl_add_u64 v[8:9], v[8:9], 2, v[4:5]
	global_load_dword v8, v[8:9], off nt
	v_cndmask_b32_e64 v9, 0, 1, s[12:13]
	v_cmp_ne_u32_e64 s[4:5], 1, v9
	s_andn2_b64 vcc, exec, s[12:13]
	s_cbranch_vccnz .LBB0_10
	global_load_dword v1, v[6:7], off offset:8
.LBB0_10:
	v_or_b32_e32 v9, 2, v2
	v_mad_i64_i32 v[10:11], s[12:13], v9, s9, 0
	v_lshl_add_u64 v[10:11], v[10:11], 2, v[4:5]
	global_load_dword v9, v[10:11], off nt
	v_mov_b32_e32 v10, 1.0
	s_and_b64 vcc, exec, s[4:5]
	v_mov_b32_e32 v11, 1.0
	s_cbranch_vccnz .LBB0_12
	global_load_dword v11, v[6:7], off offset:16
.LBB0_12:
	v_or_b32_e32 v12, 4, v2
	v_mad_i64_i32 v[12:13], s[12:13], v12, s9, 0
	v_lshl_add_u64 v[12:13], v[12:13], 2, v[4:5]
	global_load_dword v12, v[12:13], off nt
	s_and_b64 vcc, exec, s[4:5]
	s_cbranch_vccnz .LBB0_14
	global_load_dword v10, v[6:7], off offset:24
.LBB0_14:
	v_or_b32_e32 v13, 6, v2
	v_mad_i64_i32 v[14:15], s[12:13], v13, s9, 0
	v_lshl_add_u64 v[14:15], v[14:15], 2, v[4:5]
	global_load_dword v13, v[14:15], off nt
	v_mov_b32_e32 v14, 1.0
	s_and_b64 vcc, exec, s[4:5]
	v_mov_b32_e32 v15, 1.0
	s_cbranch_vccnz .LBB0_16
	global_load_dword v15, v[6:7], off offset:32
.LBB0_16:
	v_or_b32_e32 v16, 8, v2
	v_mad_i64_i32 v[16:17], s[12:13], v16, s9, 0
	v_lshl_add_u64 v[16:17], v[16:17], 2, v[4:5]
	global_load_dword v16, v[16:17], off nt
	s_and_b64 vcc, exec, s[4:5]
	s_cbranch_vccnz .LBB0_18
	global_load_dword v14, v[6:7], off offset:40
.LBB0_18:
	v_or_b32_e32 v17, 10, v2
	v_mad_i64_i32 v[18:19], s[12:13], v17, s9, 0
	v_lshl_add_u64 v[18:19], v[18:19], 2, v[4:5]
	global_load_dword v17, v[18:19], off nt
	v_mov_b32_e32 v18, 1.0
	s_and_b64 vcc, exec, s[4:5]
	v_mov_b32_e32 v19, 1.0
	s_cbranch_vccnz .LBB0_20
	global_load_dword v19, v[6:7], off offset:48
.LBB0_20:
	v_or_b32_e32 v20, 12, v2
	v_mad_i64_i32 v[20:21], s[12:13], v20, s9, 0
	v_lshl_add_u64 v[20:21], v[20:21], 2, v[4:5]
	global_load_dword v20, v[20:21], off nt
	s_and_b64 vcc, exec, s[4:5]
	s_cbranch_vccnz .LBB0_22
	global_load_dword v18, v[6:7], off offset:56
.LBB0_22:
	v_or_b32_e32 v21, 14, v2
	v_mad_i64_i32 v[22:23], s[12:13], v21, s9, 0
	v_lshl_add_u64 v[22:23], v[22:23], 2, v[4:5]
	global_load_dword v21, v[22:23], off nt
	v_mov_b32_e32 v22, 1.0
	s_and_b64 vcc, exec, s[4:5]
	v_mov_b32_e32 v23, 1.0
	s_cbranch_vccnz .LBB0_24
	global_load_dword v23, v[6:7], off offset:64
.LBB0_24:
	v_or_b32_e32 v24, 16, v2
	v_mad_i64_i32 v[24:25], s[12:13], v24, s9, 0
	v_lshl_add_u64 v[24:25], v[24:25], 2, v[4:5]
	global_load_dword v24, v[24:25], off nt
	s_and_b64 vcc, exec, s[4:5]
	s_cbranch_vccnz .LBB0_26
	global_load_dword v22, v[6:7], off offset:72
.LBB0_26:
	v_or_b32_e32 v25, 18, v2
	v_mad_i64_i32 v[26:27], s[12:13], v25, s9, 0
	v_lshl_add_u64 v[26:27], v[26:27], 2, v[4:5]
	global_load_dword v25, v[26:27], off nt
	v_mov_b32_e32 v26, 1.0
	s_and_b64 vcc, exec, s[4:5]
	v_mov_b32_e32 v27, 1.0
	s_cbranch_vccnz .LBB0_28
	global_load_dword v27, v[6:7], off offset:80
.LBB0_28:
	v_or_b32_e32 v28, 20, v2
	v_mad_i64_i32 v[28:29], s[12:13], v28, s9, 0
	v_lshl_add_u64 v[28:29], v[28:29], 2, v[4:5]
	global_load_dword v28, v[28:29], off nt
	s_and_b64 vcc, exec, s[4:5]
	s_cbranch_vccnz .LBB0_30
	global_load_dword v26, v[6:7], off offset:88
.LBB0_30:
	v_or_b32_e32 v29, 22, v2
	v_mad_i64_i32 v[30:31], s[12:13], v29, s9, 0
	v_lshl_add_u64 v[30:31], v[30:31], 2, v[4:5]
	global_load_dword v29, v[30:31], off nt
	v_mov_b32_e32 v30, 1.0
	s_and_b64 vcc, exec, s[4:5]
	v_mov_b32_e32 v31, 1.0
	s_cbranch_vccnz .LBB0_32
	global_load_dword v31, v[6:7], off offset:96
.LBB0_32:
	v_or_b32_e32 v32, 24, v2
	v_mad_i64_i32 v[36:37], s[12:13], v32, s9, 0
	v_lshl_add_u64 v[36:37], v[36:37], 2, v[4:5]
	global_load_dword v32, v[36:37], off nt
	s_and_b64 vcc, exec, s[4:5]
	s_cbranch_vccnz .LBB0_34
	global_load_dword v30, v[6:7], off offset:104
.LBB0_34:
	v_or_b32_e32 v35, 26, v2
	v_mad_i64_i32 v[36:37], s[12:13], v35, s9, 0
	v_lshl_add_u64 v[36:37], v[36:37], 2, v[4:5]
	global_load_dword v35, v[36:37], off nt
	v_mov_b32_e32 v36, 1.0
	s_and_b64 vcc, exec, s[4:5]
	v_mov_b32_e32 v37, 1.0
	s_cbranch_vccnz .LBB0_36
	global_load_dword v37, v[6:7], off offset:112
.LBB0_36:
	v_or_b32_e32 v39, 28, v2
	v_mad_i64_i32 v[40:41], s[12:13], v39, s9, 0
	v_lshl_add_u64 v[40:41], v[40:41], 2, v[4:5]
	global_load_dword v39, v[40:41], off nt
	s_and_b64 vcc, exec, s[4:5]
	s_cbranch_vccnz .LBB0_38
	global_load_dword v36, v[6:7], off offset:120
.LBB0_38:
	v_or_b32_e32 v40, 30, v2
	v_mad_i64_i32 v[40:41], s[12:13], v40, s9, 0
	v_lshl_add_u64 v[40:41], v[40:41], 2, v[4:5]
	global_load_dword v40, v[40:41], off nt
	v_mov_b32_e32 v41, 1.0
	s_and_b64 vcc, exec, s[4:5]
	v_mov_b32_e32 v42, 1.0
	s_cbranch_vccnz .LBB0_40
	global_load_dword v42, v[6:7], off offset:128
.LBB0_40:
	v_or_b32_e32 v43, 32, v2
	v_mad_i64_i32 v[44:45], s[12:13], v43, s9, 0
	v_lshl_add_u64 v[44:45], v[44:45], 2, v[4:5]
	global_load_dword v43, v[44:45], off nt
	s_and_b64 vcc, exec, s[4:5]
	s_cbranch_vccnz .LBB0_42
	global_load_dword v41, v[6:7], off offset:136
.LBB0_42:
	v_or_b32_e32 v44, 34, v2
	v_mad_i64_i32 v[44:45], s[12:13], v44, s9, 0
	v_lshl_add_u64 v[44:45], v[44:45], 2, v[4:5]
	global_load_dword v44, v[44:45], off nt
	v_mov_b32_e32 v45, 1.0
	s_and_b64 vcc, exec, s[4:5]
	v_mov_b32_e32 v46, 1.0
	s_cbranch_vccnz .LBB0_44
	global_load_dword v46, v[6:7], off offset:144
.LBB0_44:
	v_or_b32_e32 v47, 36, v2
	v_mad_i64_i32 v[48:49], s[12:13], v47, s9, 0
	v_lshl_add_u64 v[48:49], v[48:49], 2, v[4:5]
	global_load_dword v47, v[48:49], off nt
	s_and_b64 vcc, exec, s[4:5]
	s_cbranch_vccnz .LBB0_46
	global_load_dword v45, v[6:7], off offset:152
.LBB0_46:
	v_or_b32_e32 v48, 38, v2
	v_mad_i64_i32 v[48:49], s[12:13], v48, s9, 0
	v_lshl_add_u64 v[48:49], v[48:49], 2, v[4:5]
	global_load_dword v48, v[48:49], off nt
	v_mov_b32_e32 v49, 1.0
	s_and_b64 vcc, exec, s[4:5]
	v_mov_b32_e32 v50, 1.0
	s_cbranch_vccnz .LBB0_48
	global_load_dword v50, v[6:7], off offset:160
.LBB0_48:
	v_or_b32_e32 v51, 40, v2
	v_mad_i64_i32 v[52:53], s[12:13], v51, s9, 0
	v_lshl_add_u64 v[52:53], v[52:53], 2, v[4:5]
	global_load_dword v51, v[52:53], off nt
	s_and_b64 vcc, exec, s[4:5]
	s_cbranch_vccnz .LBB0_50
	global_load_dword v49, v[6:7], off offset:168
.LBB0_50:
	v_or_b32_e32 v52, 42, v2
	v_mad_i64_i32 v[52:53], s[12:13], v52, s9, 0
	v_lshl_add_u64 v[52:53], v[52:53], 2, v[4:5]
	global_load_dword v52, v[52:53], off nt
	v_mov_b32_e32 v53, 1.0
	s_and_b64 vcc, exec, s[4:5]
	v_mov_b32_e32 v54, 1.0
	s_cbranch_vccnz .LBB0_52
	global_load_dword v54, v[6:7], off offset:176
.LBB0_52:
	v_or_b32_e32 v55, 44, v2
	v_mad_i64_i32 v[56:57], s[12:13], v55, s9, 0
	v_lshl_add_u64 v[56:57], v[56:57], 2, v[4:5]
	global_load_dword v55, v[56:57], off nt
	s_and_b64 vcc, exec, s[4:5]
	s_cbranch_vccnz .LBB0_54
	global_load_dword v53, v[6:7], off offset:184
.LBB0_54:
	v_or_b32_e32 v56, 46, v2
	v_mad_i64_i32 v[56:57], s[12:13], v56, s9, 0
	v_lshl_add_u64 v[56:57], v[56:57], 2, v[4:5]
	global_load_dword v56, v[56:57], off nt
	v_mov_b32_e32 v57, 1.0
	s_and_b64 vcc, exec, s[4:5]
	v_mov_b32_e32 v58, 1.0
	s_cbranch_vccnz .LBB0_56
	global_load_dword v58, v[6:7], off offset:192
.LBB0_56:
	v_or_b32_e32 v59, 48, v2
	v_mad_i64_i32 v[60:61], s[12:13], v59, s9, 0
	v_lshl_add_u64 v[60:61], v[60:61], 2, v[4:5]
	global_load_dword v59, v[60:61], off nt
	s_and_b64 vcc, exec, s[4:5]
	s_cbranch_vccnz .LBB0_58
	global_load_dword v57, v[6:7], off offset:200
.LBB0_58:
	v_or_b32_e32 v60, 50, v2
	v_mad_i64_i32 v[60:61], s[12:13], v60, s9, 0
	v_lshl_add_u64 v[60:61], v[60:61], 2, v[4:5]
	global_load_dword v60, v[60:61], off nt
	v_mov_b32_e32 v61, 1.0
	s_and_b64 vcc, exec, s[4:5]
	v_mov_b32_e32 v62, 1.0
	s_cbranch_vccnz .LBB0_60
	global_load_dword v62, v[6:7], off offset:208
.LBB0_60:
	v_or_b32_e32 v63, 52, v2
	v_mad_i64_i32 v[64:65], s[12:13], v63, s9, 0
	v_lshl_add_u64 v[64:65], v[64:65], 2, v[4:5]
	global_load_dword v63, v[64:65], off nt
	s_and_b64 vcc, exec, s[4:5]
	s_cbranch_vccnz .LBB0_62
	global_load_dword v61, v[6:7], off offset:216
.LBB0_62:
	v_or_b32_e32 v64, 54, v2
	v_mad_i64_i32 v[64:65], s[12:13], v64, s9, 0
	v_lshl_add_u64 v[64:65], v[64:65], 2, v[4:5]
	global_load_dword v64, v[64:65], off nt
	v_mov_b32_e32 v65, 1.0
	s_and_b64 vcc, exec, s[4:5]
	v_mov_b32_e32 v66, 1.0
	s_cbranch_vccnz .LBB0_64
	global_load_dword v66, v[6:7], off offset:224
.LBB0_64:
	v_or_b32_e32 v67, 56, v2
	v_mad_i64_i32 v[68:69], s[12:13], v67, s9, 0
	v_lshl_add_u64 v[68:69], v[68:69], 2, v[4:5]
	global_load_dword v67, v[68:69], off nt
	s_and_b64 vcc, exec, s[4:5]
	s_cbranch_vccnz .LBB0_66
	global_load_dword v65, v[6:7], off offset:232
.LBB0_66:
	v_or_b32_e32 v68, 58, v2
	v_mad_i64_i32 v[68:69], s[12:13], v68, s9, 0
	v_lshl_add_u64 v[68:69], v[68:69], 2, v[4:5]
	global_load_dword v69, v[68:69], off nt
	v_mov_b32_e32 v68, 1.0
	s_and_b64 vcc, exec, s[4:5]
	v_mov_b32_e32 v70, 1.0
	s_cbranch_vccnz .LBB0_68
	global_load_dword v70, v[6:7], off offset:240
.LBB0_68:
	v_or_b32_e32 v71, 60, v2
	v_mad_i64_i32 v[72:73], s[12:13], v71, s9, 0
	v_lshl_add_u64 v[72:73], v[72:73], 2, v[4:5]
	global_load_dword v71, v[72:73], off nt
	s_and_b64 vcc, exec, s[4:5]
	s_cbranch_vccnz .LBB0_70
	global_load_dword v68, v[6:7], off offset:248

.LBB0_79:
	s_xor_b64 s[14:15], s[14:15], -1
	s_and_b64 s[4:5], s[4:5], exec
	s_mul_i32 s20, s20, s18
	s_cselect_b32 s21, s29, s27
	s_cselect_b32 s22, s28, s26
	s_sub_i32 s4, s19, s20
	s_lshl_b32 s4, s4, 5
	s_ashr_i32 s5, s4, 31
	s_lshl_b64 s[4:5], s[4:5], 2
	s_add_u32 s4, s22, s4
	s_addc_u32 s5, s21, s5
	v_lshl_add_u64 v[4:5], s[4:5], 0, v[34:35]
	v_mad_i64_i32 v[8:9], s[4:5], v2, s17, 0
	v_lshl_add_u64 v[8:9], v[8:9], 2, v[4:5]
	global_load_dword v8, v[8:9], off nt
	v_cndmask_b32_e64 v9, 0, 1, s[14:15]
	v_cmp_ne_u32_e64 s[4:5], 1, v9
	s_andn2_b64 vcc, exec, s[14:15]
	s_cbranch_vccnz .LBB0_81
	global_load_dword v1, v[6:7], off offset:8
.LBB0_81:
	v_or_b32_e32 v9, 2, v2
	v_mad_i64_i32 v[10:11], s[14:15], v9, s17, 0
	v_lshl_add_u64 v[10:11], v[10:11], 2, v[4:5]
	global_load_dword v9, v[10:11], off nt
	v_mov_b32_e32 v10, 1.0
	s_and_b64 vcc, exec, s[4:5]
	v_mov_b32_e32 v11, 1.0
	s_cbranch_vccnz .LBB0_83
	global_load_dword v11, v[6:7], off offset:16
.LBB0_83:
	v_or_b32_e32 v12, 4, v2
	v_mad_i64_i32 v[12:13], s[14:15], v12, s17, 0
	v_lshl_add_u64 v[12:13], v[12:13], 2, v[4:5]
	global_load_dword v12, v[12:13], off nt
	s_and_b64 vcc, exec, s[4:5]
	s_cbranch_vccnz .LBB0_85
	global_load_dword v10, v[6:7], off offset:24
.LBB0_85:
	v_or_b32_e32 v13, 6, v2
	v_mad_i64_i32 v[14:15], s[14:15], v13, s17, 0
	v_lshl_add_u64 v[14:15], v[14:15], 2, v[4:5]
	global_load_dword v13, v[14:15], off nt
	v_mov_b32_e32 v14, 1.0
	s_and_b64 vcc, exec, s[4:5]
	v_mov_b32_e32 v15, 1.0
	s_cbranch_vccnz .LBB0_87
	global_load_dword v15, v[6:7], off offset:32
.LBB0_87:
	v_or_b32_e32 v16, 8, v2
	v_mad_i64_i32 v[16:17], s[14:15], v16, s17, 0
	v_lshl_add_u64 v[16:17], v[16:17], 2, v[4:5]
	global_load_dword v16, v[16:17], off nt
	s_and_b64 vcc, exec, s[4:5]
	s_cbranch_vccnz .LBB0_89
	global_load_dword v14, v[6:7], off offset:40
.LBB0_89:
	v_or_b32_e32 v17, 10, v2
	v_mad_i64_i32 v[18:19], s[14:15], v17, s17, 0
	v_lshl_add_u64 v[18:19], v[18:19], 2, v[4:5]
	global_load_dword v17, v[18:19], off nt
	v_mov_b32_e32 v18, 1.0
	s_and_b64 vcc, exec, s[4:5]
	v_mov_b32_e32 v19, 1.0
	s_cbranch_vccnz .LBB0_91
	global_load_dword v19, v[6:7], off offset:48
.LBB0_91:
	v_or_b32_e32 v20, 12, v2
	v_mad_i64_i32 v[20:21], s[14:15], v20, s17, 0
	v_lshl_add_u64 v[20:21], v[20:21], 2, v[4:5]
	global_load_dword v20, v[20:21], off nt
	s_and_b64 vcc, exec, s[4:5]
	s_cbranch_vccnz .LBB0_93
	global_load_dword v18, v[6:7], off offset:56
.LBB0_93:
	v_or_b32_e32 v21, 14, v2
	v_mad_i64_i32 v[22:23], s[14:15], v21, s17, 0
	v_lshl_add_u64 v[22:23], v[22:23], 2, v[4:5]
	global_load_dword v21, v[22:23], off nt
	v_mov_b32_e32 v22, 1.0
	s_and_b64 vcc, exec, s[4:5]
	v_mov_b32_e32 v23, 1.0
	s_cbranch_vccnz .LBB0_95
	global_load_dword v23, v[6:7], off offset:64
.LBB0_95:
	v_or_b32_e32 v24, 16, v2
	v_mad_i64_i32 v[24:25], s[14:15], v24, s17, 0
	v_lshl_add_u64 v[24:25], v[24:25], 2, v[4:5]
	global_load_dword v24, v[24:25], off nt
	s_and_b64 vcc, exec, s[4:5]
	s_cbranch_vccnz .LBB0_97
	global_load_dword v22, v[6:7], off offset:72
.LBB0_97:
	v_or_b32_e32 v25, 18, v2
	v_mad_i64_i32 v[26:27], s[14:15], v25, s17, 0
	v_lshl_add_u64 v[26:27], v[26:27], 2, v[4:5]
	global_load_dword v25, v[26:27], off nt
	v_mov_b32_e32 v26, 1.0
	s_and_b64 vcc, exec, s[4:5]
	v_mov_b32_e32 v27, 1.0
	s_cbranch_vccnz .LBB0_99
	global_load_dword v27, v[6:7], off offset:80
.LBB0_99:
	v_or_b32_e32 v28, 20, v2
	v_mad_i64_i32 v[28:29], s[14:15], v28, s17, 0
	v_lshl_add_u64 v[28:29], v[28:29], 2, v[4:5]
	global_load_dword v28, v[28:29], off nt
	s_and_b64 vcc, exec, s[4:5]
	s_cbranch_vccnz .LBB0_101
	global_load_dword v26, v[6:7], off offset:88
.LBB0_101:
	v_or_b32_e32 v29, 22, v2
	v_mad_i64_i32 v[30:31], s[14:15], v29, s17, 0
	v_lshl_add_u64 v[30:31], v[30:31], 2, v[4:5]
	global_load_dword v29, v[30:31], off nt
	v_mov_b32_e32 v30, 1.0
	s_and_b64 vcc, exec, s[4:5]
	v_mov_b32_e32 v31, 1.0
	s_cbranch_vccnz .LBB0_103
	global_load_dword v31, v[6:7], off offset:96
.LBB0_103:
	v_or_b32_e32 v32, 24, v2
	v_mad_i64_i32 v[52:53], s[14:15], v32, s17, 0
	v_lshl_add_u64 v[52:53], v[52:53], 2, v[4:5]
	global_load_dword v32, v[52:53], off nt
	s_and_b64 vcc, exec, s[4:5]
	s_cbranch_vccnz .LBB0_105
	global_load_dword v30, v[6:7], off offset:104
.LBB0_105:
	v_or_b32_e32 v37, 26, v2
	v_mad_i64_i32 v[52:53], s[14:15], v37, s17, 0
	v_lshl_add_u64 v[52:53], v[52:53], 2, v[4:5]
	global_load_dword v37, v[52:53], off nt
	v_mov_b32_e32 v52, 1.0
	s_and_b64 vcc, exec, s[4:5]
	v_mov_b32_e32 v53, 1.0
	s_cbranch_vccnz .LBB0_107
	global_load_dword v53, v[6:7], off offset:112
.LBB0_107:
	v_or_b32_e32 v54, 28, v2
	v_mad_i64_i32 v[54:55], s[14:15], v54, s17, 0
	v_lshl_add_u64 v[54:55], v[54:55], 2, v[4:5]
	global_load_dword v54, v[54:55], off nt
	s_and_b64 vcc, exec, s[4:5]
	s_cbranch_vccnz .LBB0_109
	global_load_dword v52, v[6:7], off offset:120
.LBB0_109:
	v_or_b32_e32 v55, 30, v2
	v_mad_i64_i32 v[56:57], s[14:15], v55, s17, 0
	v_lshl_add_u64 v[56:57], v[56:57], 2, v[4:5]
	global_load_dword v55, v[56:57], off nt
	v_mov_b32_e32 v56, 1.0
	s_and_b64 vcc, exec, s[4:5]
	v_mov_b32_e32 v57, 1.0
	s_cbranch_vccnz .LBB0_111
	global_load_dword v57, v[6:7], off offset:128
.LBB0_111:
	v_or_b32_e32 v58, 32, v2
	v_mad_i64_i32 v[58:59], s[14:15], v58, s17, 0
	v_lshl_add_u64 v[58:59], v[58:59], 2, v[4:5]
	global_load_dword v58, v[58:59], off nt
	s_and_b64 vcc, exec, s[4:5]
	s_cbranch_vccnz .LBB0_113
	global_load_dword v56, v[6:7], off offset:136
.LBB0_113:
	v_or_b32_e32 v59, 34, v2
	v_mad_i64_i32 v[60:61], s[14:15], v59, s17, 0
	v_lshl_add_u64 v[60:61], v[60:61], 2, v[4:5]
	global_load_dword v59, v[60:61], off nt
	v_mov_b32_e32 v60, 1.0
	s_and_b64 vcc, exec, s[4:5]
	v_mov_b32_e32 v61, 1.0
	s_cbranch_vccnz .LBB0_115
	global_load_dword v61, v[6:7], off offset:144
.LBB0_115:
	v_or_b32_e32 v62, 36, v2
	v_mad_i64_i32 v[62:63], s[14:15], v62, s17, 0
	v_lshl_add_u64 v[62:63], v[62:63], 2, v[4:5]
	global_load_dword v62, v[62:63], off nt
	s_and_b64 vcc, exec, s[4:5]
	s_cbranch_vccnz .LBB0_117
	global_load_dword v60, v[6:7], off offset:152
.LBB0_117:
	v_or_b32_e32 v63, 38, v2
	v_mad_i64_i32 v[64:65], s[14:15], v63, s17, 0
	v_lshl_add_u64 v[64:65], v[64:65], 2, v[4:5]
	global_load_dword v63, v[64:65], off nt
	v_mov_b32_e32 v64, 1.0
	s_and_b64 vcc, exec, s[4:5]
	v_mov_b32_e32 v65, 1.0
	s_cbranch_vccnz .LBB0_119
	global_load_dword v65, v[6:7], off offset:160
.LBB0_119:
	v_or_b32_e32 v66, 40, v2
	v_mad_i64_i32 v[66:67], s[14:15], v66, s17, 0
	v_lshl_add_u64 v[66:67], v[66:67], 2, v[4:5]
	global_load_dword v66, v[66:67], off nt
	s_and_b64 vcc, exec, s[4:5]
	s_cbranch_vccnz .LBB0_121
	global_load_dword v64, v[6:7], off offset:168
.LBB0_121:
	v_or_b32_e32 v67, 42, v2
	v_mad_i64_i32 v[68:69], s[14:15], v67, s17, 0
	v_lshl_add_u64 v[68:69], v[68:69], 2, v[4:5]
	global_load_dword v67, v[68:69], off nt
	v_mov_b32_e32 v68, 1.0
	s_and_b64 vcc, exec, s[4:5]
	v_mov_b32_e32 v69, 1.0
	s_cbranch_vccnz .LBB0_123
	global_load_dword v69, v[6:7], off offset:176
.LBB0_123:
	v_or_b32_e32 v70, 44, v2
	v_mad_i64_i32 v[70:71], s[14:15], v70, s17, 0
	v_lshl_add_u64 v[70:71], v[70:71], 2, v[4:5]
	global_load_dword v70, v[70:71], off nt
	s_and_b64 vcc, exec, s[4:5]
	s_cbranch_vccnz .LBB0_125
	global_load_dword v68, v[6:7], off offset:184
.LBB0_125:
	v_or_b32_e32 v71, 46, v2
	v_mad_i64_i32 v[72:73], s[14:15], v71, s17, 0
	v_lshl_add_u64 v[72:73], v[72:73], 2, v[4:5]
	global_load_dword v71, v[72:73], off nt
	v_mov_b32_e32 v72, 1.0
	s_and_b64 vcc, exec, s[4:5]
	v_mov_b32_e32 v73, 1.0
	s_cbranch_vccnz .LBB0_127
	global_load_dword v73, v[6:7], off offset:192
.LBB0_127:
	v_or_b32_e32 v74, 48, v2
	v_mad_i64_i32 v[74:75], s[14:15], v74, s17, 0
	v_lshl_add_u64 v[74:75], v[74:75], 2, v[4:5]
	global_load_dword v74, v[74:75], off nt
	s_and_b64 vcc, exec, s[4:5]
	s_cbranch_vccnz .LBB0_129
	global_load_dword v72, v[6:7], off offset:200
.LBB0_129:
	v_or_b32_e32 v75, 50, v2
	v_mad_i64_i32 v[76:77], s[14:15], v75, s17, 0
	v_lshl_add_u64 v[76:77], v[76:77], 2, v[4:5]
	global_load_dword v75, v[76:77], off nt
	v_mov_b32_e32 v76, 1.0
	s_and_b64 vcc, exec, s[4:5]
	v_mov_b32_e32 v77, 1.0
	s_cbranch_vccnz .LBB0_131
	global_load_dword v77, v[6:7], off offset:208
.LBB0_131:
	v_or_b32_e32 v78, 52, v2
	v_mad_i64_i32 v[78:79], s[14:15], v78, s17, 0
	v_lshl_add_u64 v[78:79], v[78:79], 2, v[4:5]
	global_load_dword v78, v[78:79], off nt
	s_and_b64 vcc, exec, s[4:5]
	s_cbranch_vccnz .LBB0_133
	global_load_dword v76, v[6:7], off offset:216
.LBB0_133:
	v_or_b32_e32 v79, 54, v2
	v_mad_i64_i32 v[80:81], s[14:15], v79, s17, 0
	v_lshl_add_u64 v[80:81], v[80:81], 2, v[4:5]
	global_load_dword v79, v[80:81], off nt
	v_mov_b32_e32 v80, 1.0
	s_and_b64 vcc, exec, s[4:5]
	v_mov_b32_e32 v81, 1.0
	s_cbranch_vccnz .LBB0_135
	global_load_dword v81, v[6:7], off offset:224
.LBB0_135:
	v_or_b32_e32 v82, 56, v2
	v_mad_i64_i32 v[82:83], s[14:15], v82, s17, 0
	v_lshl_add_u64 v[82:83], v[82:83], 2, v[4:5]
	global_load_dword v82, v[82:83], off nt
	s_and_b64 vcc, exec, s[4:5]
	s_cbranch_vccnz .LBB0_137
	global_load_dword v80, v[6:7], off offset:232
.LBB0_137:
	v_or_b32_e32 v83, 58, v2
	v_mad_i64_i32 v[84:85], s[14:15], v83, s17, 0
	v_lshl_add_u64 v[84:85], v[84:85], 2, v[4:5]
	global_load_dword v84, v[84:85], off nt
	v_mov_b32_e32 v83, 1.0
	s_and_b64 vcc, exec, s[4:5]
	v_mov_b32_e32 v85, 1.0
	s_cbranch_vccnz .LBB0_139
	global_load_dword v85, v[6:7], off offset:240
.LBB0_139:
	v_or_b32_e32 v86, 60, v2
	v_mad_i64_i32 v[86:87], s[14:15], v86, s17, 0
	v_lshl_add_u64 v[86:87], v[86:87], 2, v[4:5]
	global_load_dword v86, v[86:87], off nt
	s_and_b64 vcc, exec, s[4:5]
	s_cbranch_vccnz .LBB0_74
	global_load_dword v83, v[6:7], off offset:248
	s_branch .LBB0_74

.LBB0_168:
	s_xor_b64 s[10:11], s[10:11], -1
	s_and_b64 s[4:5], s[4:5], exec
	s_mul_i32 s21, s21, s19
	s_cselect_b32 s22, s17, s15
	s_cselect_b32 s23, s16, s14
	s_sub_i32 s4, s20, s21
	s_lshl_b32 s4, s4, 5
	s_ashr_i32 s5, s4, 31
	s_lshl_b64 s[4:5], s[4:5], 2
	v_and_b32_e32 v0, 31, v37
	s_add_u32 s4, s23, s4
	s_addc_u32 s5, s22, s5
	v_lshlrev_b32_e32 v0, 2, v0
	v_lshl_add_u64 v[4:5], s[4:5], 0, v[0:1]
	v_mad_i64_i32 v[10:11], s[4:5], v2, s18, 0
	v_lshl_add_u64 v[10:11], v[10:11], 2, v[4:5]
	global_load_dword v0, v[10:11], off nt
	v_cndmask_b32_e64 v9, 0, 1, s[10:11]
	v_cmp_ne_u32_e64 s[4:5], 1, v9
	s_andn2_b64 vcc, exec, s[10:11]
	s_cbranch_vccnz .LBB0_170
	global_load_dword v8, v[6:7], off offset:8
.LBB0_170:
	v_or_b32_e32 v9, 2, v2
	v_mad_i64_i32 v[10:11], s[10:11], v9, s18, 0
	v_lshl_add_u64 v[10:11], v[10:11], 2, v[4:5]
	global_load_dword v9, v[10:11], off nt
	v_mov_b32_e32 v10, 1.0
	s_and_b64 vcc, exec, s[4:5]
	v_mov_b32_e32 v11, 1.0
	s_cbranch_vccnz .LBB0_172
	global_load_dword v11, v[6:7], off offset:16
.LBB0_172:
	v_or_b32_e32 v12, 4, v2
	v_mad_i64_i32 v[12:13], s[10:11], v12, s18, 0
	v_lshl_add_u64 v[12:13], v[12:13], 2, v[4:5]
	global_load_dword v12, v[12:13], off nt
	s_and_b64 vcc, exec, s[4:5]
	s_cbranch_vccnz .LBB0_174
	global_load_dword v10, v[6:7], off offset:24
.LBB0_174:
	v_or_b32_e32 v13, 6, v2
	v_mad_i64_i32 v[14:15], s[10:11], v13, s18, 0
	v_lshl_add_u64 v[14:15], v[14:15], 2, v[4:5]
	global_load_dword v13, v[14:15], off nt
	v_mov_b32_e32 v14, 1.0
	s_and_b64 vcc, exec, s[4:5]
	v_mov_b32_e32 v15, 1.0
	s_cbranch_vccnz .LBB0_176
	global_load_dword v15, v[6:7], off offset:32
.LBB0_176:
	v_or_b32_e32 v16, 8, v2
	v_mad_i64_i32 v[16:17], s[10:11], v16, s18, 0
	v_lshl_add_u64 v[16:17], v[16:17], 2, v[4:5]
	global_load_dword v16, v[16:17], off nt
	s_and_b64 vcc, exec, s[4:5]
	s_cbranch_vccnz .LBB0_178
	global_load_dword v14, v[6:7], off offset:40
.LBB0_178:
	v_or_b32_e32 v17, 10, v2
	v_mad_i64_i32 v[18:19], s[10:11], v17, s18, 0
	v_lshl_add_u64 v[18:19], v[18:19], 2, v[4:5]
	global_load_dword v17, v[18:19], off nt
	v_mov_b32_e32 v18, 1.0
	s_and_b64 vcc, exec, s[4:5]
	v_mov_b32_e32 v19, 1.0
	s_cbranch_vccnz .LBB0_180
	global_load_dword v19, v[6:7], off offset:48
.LBB0_180:
	v_or_b32_e32 v20, 12, v2
	v_mad_i64_i32 v[20:21], s[10:11], v20, s18, 0
	v_lshl_add_u64 v[20:21], v[20:21], 2, v[4:5]
	global_load_dword v20, v[20:21], off nt
	s_and_b64 vcc, exec, s[4:5]
	s_cbranch_vccnz .LBB0_182
	global_load_dword v18, v[6:7], off offset:56
.LBB0_182:
	v_or_b32_e32 v21, 14, v2
	v_mad_i64_i32 v[22:23], s[10:11], v21, s18, 0
	v_lshl_add_u64 v[22:23], v[22:23], 2, v[4:5]
	global_load_dword v21, v[22:23], off nt
	v_mov_b32_e32 v22, 1.0
	s_and_b64 vcc, exec, s[4:5]
	v_mov_b32_e32 v23, 1.0
	s_cbranch_vccnz .LBB0_184
	global_load_dword v23, v[6:7], off offset:64
.LBB0_184:
	v_or_b32_e32 v24, 16, v2
	v_mad_i64_i32 v[24:25], s[10:11], v24, s18, 0
	v_lshl_add_u64 v[24:25], v[24:25], 2, v[4:5]
	global_load_dword v24, v[24:25], off nt
	s_and_b64 vcc, exec, s[4:5]
	s_cbranch_vccnz .LBB0_186
	global_load_dword v22, v[6:7], off offset:72
.LBB0_186:
	v_or_b32_e32 v25, 18, v2
	v_mad_i64_i32 v[26:27], s[10:11], v25, s18, 0
	v_lshl_add_u64 v[26:27], v[26:27], 2, v[4:5]
	global_load_dword v25, v[26:27], off nt
	v_mov_b32_e32 v26, 1.0
	s_and_b64 vcc, exec, s[4:5]
	v_mov_b32_e32 v27, 1.0
	s_cbranch_vccnz .LBB0_188
	global_load_dword v27, v[6:7], off offset:80
.LBB0_188:
	v_or_b32_e32 v28, 20, v2
	v_mad_i64_i32 v[28:29], s[10:11], v28, s18, 0
	v_lshl_add_u64 v[28:29], v[28:29], 2, v[4:5]
	global_load_dword v28, v[28:29], off nt
	s_and_b64 vcc, exec, s[4:5]
	s_cbranch_vccnz .LBB0_190
	global_load_dword v26, v[6:7], off offset:88
.LBB0_190:
	v_or_b32_e32 v29, 22, v2
	v_mad_i64_i32 v[30:31], s[10:11], v29, s18, 0
	v_lshl_add_u64 v[30:31], v[30:31], 2, v[4:5]
	global_load_dword v29, v[30:31], off nt
	v_mov_b32_e32 v30, 1.0
	s_and_b64 vcc, exec, s[4:5]
	v_mov_b32_e32 v31, 1.0
	s_cbranch_vccnz .LBB0_192
	global_load_dword v31, v[6:7], off offset:96
.LBB0_192:
	v_or_b32_e32 v32, 24, v2
	v_mad_i64_i32 v[32:33], s[10:11], v32, s18, 0
	v_lshl_add_u64 v[32:33], v[32:33], 2, v[4:5]
	global_load_dword v32, v[32:33], off nt
	s_and_b64 vcc, exec, s[4:5]
	s_cbranch_vccnz .LBB0_194
	global_load_dword v30, v[6:7], off offset:104
.LBB0_194:
	v_or_b32_e32 v33, 26, v2
	v_mad_i64_i32 v[34:35], s[10:11], v33, s18, 0
	v_lshl_add_u64 v[34:35], v[34:35], 2, v[4:5]
	global_load_dword v33, v[34:35], off nt
	v_mov_b32_e32 v34, 1.0
	s_and_b64 vcc, exec, s[4:5]
	v_mov_b32_e32 v35, 1.0
	s_cbranch_vccnz .LBB0_196
	global_load_dword v35, v[6:7], off offset:112
.LBB0_196:
	v_or_b32_e32 v38, 28, v2
	v_mad_i64_i32 v[38:39], s[10:11], v38, s18, 0
	v_lshl_add_u64 v[38:39], v[38:39], 2, v[4:5]
	global_load_dword v38, v[38:39], off nt
	s_and_b64 vcc, exec, s[4:5]
	s_cbranch_vccnz .LBB0_198
	global_load_dword v34, v[6:7], off offset:120
.LBB0_198:
	v_or_b32_e32 v39, 30, v2
	v_mad_i64_i32 v[40:41], s[10:11], v39, s18, 0
	v_lshl_add_u64 v[40:41], v[40:41], 2, v[4:5]
	global_load_dword v39, v[40:41], off nt
	v_mov_b32_e32 v40, 1.0
	s_and_b64 vcc, exec, s[4:5]
	v_mov_b32_e32 v41, 1.0
	s_cbranch_vccnz .LBB0_200
	global_load_dword v41, v[6:7], off offset:128
.LBB0_200:
	v_or_b32_e32 v42, 32, v2
	v_mad_i64_i32 v[42:43], s[10:11], v42, s18, 0
	v_lshl_add_u64 v[42:43], v[42:43], 2, v[4:5]
	global_load_dword v42, v[42:43], off nt
	s_and_b64 vcc, exec, s[4:5]
	s_cbranch_vccnz .LBB0_202
	global_load_dword v40, v[6:7], off offset:136
.LBB0_202:
	v_or_b32_e32 v43, 34, v2
	v_mad_i64_i32 v[44:45], s[10:11], v43, s18, 0
	v_lshl_add_u64 v[44:45], v[44:45], 2, v[4:5]
	global_load_dword v43, v[44:45], off nt
	v_mov_b32_e32 v44, 1.0
	s_and_b64 vcc, exec, s[4:5]
	v_mov_b32_e32 v45, 1.0
	s_cbranch_vccnz .LBB0_204
	global_load_dword v45, v[6:7], off offset:144
.LBB0_204:
	v_or_b32_e32 v46, 36, v2
	v_mad_i64_i32 v[46:47], s[10:11], v46, s18, 0
	v_lshl_add_u64 v[46:47], v[46:47], 2, v[4:5]
	global_load_dword v46, v[46:47], off nt
	s_and_b64 vcc, exec, s[4:5]
	s_cbranch_vccnz .LBB0_206
	global_load_dword v44, v[6:7], off offset:152
.LBB0_206:
	v_or_b32_e32 v47, 38, v2
	v_mad_i64_i32 v[48:49], s[10:11], v47, s18, 0
	v_lshl_add_u64 v[48:49], v[48:49], 2, v[4:5]
	global_load_dword v47, v[48:49], off nt
	v_mov_b32_e32 v48, 1.0
	s_and_b64 vcc, exec, s[4:5]
	v_mov_b32_e32 v49, 1.0
	s_cbranch_vccnz .LBB0_208
	global_load_dword v49, v[6:7], off offset:160
.LBB0_208:
	v_or_b32_e32 v50, 40, v2
	v_mad_i64_i32 v[50:51], s[10:11], v50, s18, 0
	v_lshl_add_u64 v[50:51], v[50:51], 2, v[4:5]
	global_load_dword v50, v[50:51], off nt
	s_and_b64 vcc, exec, s[4:5]
	s_cbranch_vccnz .LBB0_210
	global_load_dword v48, v[6:7], off offset:168
.LBB0_210:
	v_or_b32_e32 v51, 42, v2
	v_mad_i64_i32 v[52:53], s[10:11], v51, s18, 0
	v_lshl_add_u64 v[52:53], v[52:53], 2, v[4:5]
	global_load_dword v51, v[52:53], off nt
	v_mov_b32_e32 v52, 1.0
	s_and_b64 vcc, exec, s[4:5]
	v_mov_b32_e32 v53, 1.0
	s_cbranch_vccnz .LBB0_212
	global_load_dword v53, v[6:7], off offset:176
.LBB0_212:
	v_or_b32_e32 v54, 44, v2
	v_mad_i64_i32 v[54:55], s[10:11], v54, s18, 0
	v_lshl_add_u64 v[54:55], v[54:55], 2, v[4:5]
	global_load_dword v54, v[54:55], off nt
	s_and_b64 vcc, exec, s[4:5]
	s_cbranch_vccnz .LBB0_214
	global_load_dword v52, v[6:7], off offset:184
.LBB0_214:
	v_or_b32_e32 v55, 46, v2
	v_mad_i64_i32 v[56:57], s[10:11], v55, s18, 0
	v_lshl_add_u64 v[56:57], v[56:57], 2, v[4:5]
	global_load_dword v55, v[56:57], off nt
	v_mov_b32_e32 v56, 1.0
	s_and_b64 vcc, exec, s[4:5]
	v_mov_b32_e32 v57, 1.0
	s_cbranch_vccnz .LBB0_216
	global_load_dword v57, v[6:7], off offset:192
.LBB0_216:
	v_or_b32_e32 v58, 48, v2
	v_mad_i64_i32 v[58:59], s[10:11], v58, s18, 0
	v_lshl_add_u64 v[58:59], v[58:59], 2, v[4:5]
	global_load_dword v58, v[58:59], off nt
	s_and_b64 vcc, exec, s[4:5]
	s_cbranch_vccnz .LBB0_218
	global_load_dword v56, v[6:7], off offset:200
.LBB0_218:
	v_or_b32_e32 v59, 50, v2
	v_mad_i64_i32 v[60:61], s[10:11], v59, s18, 0
	v_lshl_add_u64 v[60:61], v[60:61], 2, v[4:5]
	global_load_dword v59, v[60:61], off nt
	v_mov_b32_e32 v60, 1.0
	s_and_b64 vcc, exec, s[4:5]
	v_mov_b32_e32 v61, 1.0
	s_cbranch_vccnz .LBB0_220
	global_load_dword v61, v[6:7], off offset:208
.LBB0_220:
	v_or_b32_e32 v62, 52, v2
	v_mad_i64_i32 v[62:63], s[10:11], v62, s18, 0
	v_lshl_add_u64 v[62:63], v[62:63], 2, v[4:5]
	global_load_dword v62, v[62:63], off nt
	s_and_b64 vcc, exec, s[4:5]
	s_cbranch_vccnz .LBB0_222
	global_load_dword v60, v[6:7], off offset:216
.LBB0_222:
	v_or_b32_e32 v63, 54, v2
	v_mad_i64_i32 v[64:65], s[10:11], v63, s18, 0
	v_lshl_add_u64 v[64:65], v[64:65], 2, v[4:5]
	global_load_dword v63, v[64:65], off nt
	v_mov_b32_e32 v64, 1.0
	s_and_b64 vcc, exec, s[4:5]
	v_mov_b32_e32 v65, 1.0
	s_cbranch_vccnz .LBB0_224
	global_load_dword v65, v[6:7], off offset:224
.LBB0_224:
	v_or_b32_e32 v66, 56, v2
	v_mad_i64_i32 v[66:67], s[10:11], v66, s18, 0
	v_lshl_add_u64 v[66:67], v[66:67], 2, v[4:5]
	global_load_dword v66, v[66:67], off nt
	s_and_b64 vcc, exec, s[4:5]
	s_cbranch_vccnz .LBB0_226
	global_load_dword v64, v[6:7], off offset:232
.LBB0_226:
	v_or_b32_e32 v67, 58, v2
	v_mad_i64_i32 v[68:69], s[10:11], v67, s18, 0
	v_lshl_add_u64 v[68:69], v[68:69], 2, v[4:5]
	global_load_dword v68, v[68:69], off nt
	v_mov_b32_e32 v67, 1.0
	s_and_b64 vcc, exec, s[4:5]
	v_mov_b32_e32 v69, 1.0
	s_cbranch_vccnz .LBB0_228
	global_load_dword v69, v[6:7], off offset:240
.LBB0_228:
	v_or_b32_e32 v70, 60, v2
	v_mad_i64_i32 v[70:71], s[10:11], v70, s18, 0
	v_lshl_add_u64 v[70:71], v[70:71], 2, v[4:5]
	global_load_dword v70, v[70:71], off nt
	s_and_b64 vcc, exec, s[4:5]
	s_cbranch_vccnz .LBB0_230
	global_load_dword v67, v[6:7], off offset:248

.LBB0_238:
	s_xor_b64 s[10:11], s[10:11], -1
	s_and_b64 s[4:5], s[4:5], exec
	s_mul_i32 s23, s23, s21
	s_cselect_b32 s24, s17, s15
	s_cselect_b32 s25, s16, s14
	s_sub_i32 s4, s22, s23
	s_lshl_b32 s4, s4, 5
	s_ashr_i32 s5, s4, 31
	s_lshl_b64 s[4:5], s[4:5], 2
	s_add_u32 s4, s25, s4
	s_addc_u32 s5, s24, s5
	v_lshl_add_u64 v[4:5], s[4:5], 0, v[0:1]
	v_mad_i64_i32 v[10:11], s[4:5], v2, s20, 0
	v_lshl_add_u64 v[10:11], v[10:11], 2, v[4:5]
	global_load_dword v9, v[10:11], off nt
	v_cndmask_b32_e64 v10, 0, 1, s[10:11]
	v_cmp_ne_u32_e64 s[4:5], 1, v10
	s_andn2_b64 vcc, exec, s[10:11]
	s_cbranch_vccnz .LBB0_240
	global_load_dword v8, v[6:7], off offset:8
.LBB0_240:
	v_or_b32_e32 v10, 2, v2
	v_mad_i64_i32 v[10:11], s[10:11], v10, s20, 0
	v_lshl_add_u64 v[10:11], v[10:11], 2, v[4:5]
	global_load_dword v10, v[10:11], off nt
	v_mov_b32_e32 v11, 1.0
	s_and_b64 vcc, exec, s[4:5]
	v_mov_b32_e32 v12, 1.0
	s_cbranch_vccnz .LBB0_242
	global_load_dword v12, v[6:7], off offset:16
.LBB0_242:
	v_or_b32_e32 v13, 4, v2
	v_mad_i64_i32 v[14:15], s[10:11], v13, s20, 0
	v_lshl_add_u64 v[14:15], v[14:15], 2, v[4:5]
	global_load_dword v13, v[14:15], off nt
	s_and_b64 vcc, exec, s[4:5]
	s_cbranch_vccnz .LBB0_244
	global_load_dword v11, v[6:7], off offset:24
.LBB0_244:
	v_or_b32_e32 v14, 6, v2
	v_mad_i64_i32 v[14:15], s[10:11], v14, s20, 0
	v_lshl_add_u64 v[14:15], v[14:15], 2, v[4:5]
	global_load_dword v14, v[14:15], off nt
	v_mov_b32_e32 v15, 1.0
	s_and_b64 vcc, exec, s[4:5]
	v_mov_b32_e32 v16, 1.0
	s_cbranch_vccnz .LBB0_246
	global_load_dword v16, v[6:7], off offset:32
.LBB0_246:
	v_or_b32_e32 v17, 8, v2
	v_mad_i64_i32 v[18:19], s[10:11], v17, s20, 0
	v_lshl_add_u64 v[18:19], v[18:19], 2, v[4:5]
	global_load_dword v17, v[18:19], off nt
	s_and_b64 vcc, exec, s[4:5]
	s_cbranch_vccnz .LBB0_248
	global_load_dword v15, v[6:7], off offset:40
.LBB0_248:
	v_or_b32_e32 v18, 10, v2
	v_mad_i64_i32 v[18:19], s[10:11], v18, s20, 0
	v_lshl_add_u64 v[18:19], v[18:19], 2, v[4:5]
	global_load_dword v18, v[18:19], off nt
	v_mov_b32_e32 v19, 1.0
	s_and_b64 vcc, exec, s[4:5]
	v_mov_b32_e32 v20, 1.0
	s_cbranch_vccnz .LBB0_250
	global_load_dword v20, v[6:7], off offset:48
.LBB0_250:
	v_or_b32_e32 v21, 12, v2
	v_mad_i64_i32 v[22:23], s[10:11], v21, s20, 0
	v_lshl_add_u64 v[22:23], v[22:23], 2, v[4:5]
	global_load_dword v21, v[22:23], off nt
	s_and_b64 vcc, exec, s[4:5]
	s_cbranch_vccnz .LBB0_252
	global_load_dword v19, v[6:7], off offset:56
.LBB0_252:
	v_or_b32_e32 v22, 14, v2
	v_mad_i64_i32 v[22:23], s[10:11], v22, s20, 0
	v_lshl_add_u64 v[22:23], v[22:23], 2, v[4:5]
	global_load_dword v22, v[22:23], off nt
	v_mov_b32_e32 v23, 1.0
	s_and_b64 vcc, exec, s[4:5]
	v_mov_b32_e32 v24, 1.0
	s_cbranch_vccnz .LBB0_254
	global_load_dword v24, v[6:7], off offset:64
.LBB0_254:
	v_or_b32_e32 v25, 16, v2
	v_mad_i64_i32 v[26:27], s[10:11], v25, s20, 0
	v_lshl_add_u64 v[26:27], v[26:27], 2, v[4:5]
	global_load_dword v25, v[26:27], off nt
	s_and_b64 vcc, exec, s[4:5]
	s_cbranch_vccnz .LBB0_256
	global_load_dword v23, v[6:7], off offset:72
.LBB0_256:
	v_or_b32_e32 v26, 18, v2
	v_mad_i64_i32 v[26:27], s[10:11], v26, s20, 0
	v_lshl_add_u64 v[26:27], v[26:27], 2, v[4:5]
	global_load_dword v26, v[26:27], off nt
	v_mov_b32_e32 v27, 1.0
	s_and_b64 vcc, exec, s[4:5]
	v_mov_b32_e32 v28, 1.0
	s_cbranch_vccnz .LBB0_258
	global_load_dword v28, v[6:7], off offset:80
.LBB0_258:
	v_or_b32_e32 v29, 20, v2
	v_mad_i64_i32 v[30:31], s[10:11], v29, s20, 0
	v_lshl_add_u64 v[30:31], v[30:31], 2, v[4:5]
	global_load_dword v29, v[30:31], off nt
	s_and_b64 vcc, exec, s[4:5]
	s_cbranch_vccnz .LBB0_260
	global_load_dword v27, v[6:7], off offset:88
.LBB0_260:
	v_or_b32_e32 v30, 22, v2
	v_mad_i64_i32 v[30:31], s[10:11], v30, s20, 0
	v_lshl_add_u64 v[30:31], v[30:31], 2, v[4:5]
	global_load_dword v30, v[30:31], off nt
	v_mov_b32_e32 v31, 1.0
	s_and_b64 vcc, exec, s[4:5]
	v_mov_b32_e32 v32, 1.0
	s_cbranch_vccnz .LBB0_262
	global_load_dword v32, v[6:7], off offset:96
.LBB0_262:
	v_or_b32_e32 v33, 24, v2
	v_mad_i64_i32 v[46:47], s[10:11], v33, s20, 0
	v_lshl_add_u64 v[46:47], v[46:47], 2, v[4:5]
	global_load_dword v33, v[46:47], off nt
	s_and_b64 vcc, exec, s[4:5]
	s_cbranch_vccnz .LBB0_264
	global_load_dword v31, v[6:7], off offset:104
.LBB0_264:
	v_or_b32_e32 v35, 26, v2
	v_mad_i64_i32 v[46:47], s[10:11], v35, s20, 0
	v_lshl_add_u64 v[46:47], v[46:47], 2, v[4:5]
	global_load_dword v35, v[46:47], off nt
	v_mov_b32_e32 v45, 1.0
	s_and_b64 vcc, exec, s[4:5]
	v_mov_b32_e32 v46, 1.0
	s_cbranch_vccnz .LBB0_266
	global_load_dword v46, v[6:7], off offset:112
.LBB0_266:
	v_or_b32_e32 v47, 28, v2
	v_mad_i64_i32 v[48:49], s[10:11], v47, s20, 0
	v_lshl_add_u64 v[48:49], v[48:49], 2, v[4:5]
	global_load_dword v47, v[48:49], off nt
	s_and_b64 vcc, exec, s[4:5]
	s_cbranch_vccnz .LBB0_268
	global_load_dword v45, v[6:7], off offset:120
.LBB0_268:
	v_or_b32_e32 v48, 30, v2
	v_mad_i64_i32 v[48:49], s[10:11], v48, s20, 0
	v_lshl_add_u64 v[48:49], v[48:49], 2, v[4:5]
	global_load_dword v48, v[48:49], off nt
	v_mov_b32_e32 v49, 1.0
	s_and_b64 vcc, exec, s[4:5]
	v_mov_b32_e32 v50, 1.0
	s_cbranch_vccnz .LBB0_270
	global_load_dword v50, v[6:7], off offset:128
.LBB0_270:
	v_or_b32_e32 v51, 32, v2
	v_mad_i64_i32 v[52:53], s[10:11], v51, s20, 0
	v_lshl_add_u64 v[52:53], v[52:53], 2, v[4:5]
	global_load_dword v51, v[52:53], off nt
	s_and_b64 vcc, exec, s[4:5]
	s_cbranch_vccnz .LBB0_272
	global_load_dword v49, v[6:7], off offset:136
.LBB0_272:
	v_or_b32_e32 v52, 34, v2
	v_mad_i64_i32 v[52:53], s[10:11], v52, s20, 0
	v_lshl_add_u64 v[52:53], v[52:53], 2, v[4:5]
	global_load_dword v52, v[52:53], off nt
	v_mov_b32_e32 v53, 1.0
	s_and_b64 vcc, exec, s[4:5]
	v_mov_b32_e32 v54, 1.0
	s_cbranch_vccnz .LBB0_274
	global_load_dword v54, v[6:7], off offset:144
.LBB0_274:
	v_or_b32_e32 v55, 36, v2
	v_mad_i64_i32 v[56:57], s[10:11], v55, s20, 0
	v_lshl_add_u64 v[56:57], v[56:57], 2, v[4:5]
	global_load_dword v55, v[56:57], off nt
	s_and_b64 vcc, exec, s[4:5]
	s_cbranch_vccnz .LBB0_276
	global_load_dword v53, v[6:7], off offset:152
.LBB0_276:
	v_or_b32_e32 v56, 38, v2
	v_mad_i64_i32 v[56:57], s[10:11], v56, s20, 0
	v_lshl_add_u64 v[56:57], v[56:57], 2, v[4:5]
	global_load_dword v56, v[56:57], off nt
	v_mov_b32_e32 v57, 1.0
	s_and_b64 vcc, exec, s[4:5]
	v_mov_b32_e32 v58, 1.0
	s_cbranch_vccnz .LBB0_278
	global_load_dword v58, v[6:7], off offset:160
.LBB0_278:
	v_or_b32_e32 v59, 40, v2
	v_mad_i64_i32 v[60:61], s[10:11], v59, s20, 0
	v_lshl_add_u64 v[60:61], v[60:61], 2, v[4:5]
	global_load_dword v59, v[60:61], off nt
	s_and_b64 vcc, exec, s[4:5]
	s_cbranch_vccnz .LBB0_280
	global_load_dword v57, v[6:7], off offset:168
.LBB0_280:
	v_or_b32_e32 v60, 42, v2
	v_mad_i64_i32 v[60:61], s[10:11], v60, s20, 0
	v_lshl_add_u64 v[60:61], v[60:61], 2, v[4:5]
	global_load_dword v60, v[60:61], off nt
	v_mov_b32_e32 v61, 1.0
	s_and_b64 vcc, exec, s[4:5]
	v_mov_b32_e32 v62, 1.0
	s_cbranch_vccnz .LBB0_282
	global_load_dword v62, v[6:7], off offset:176
.LBB0_282:
	v_or_b32_e32 v63, 44, v2
	v_mad_i64_i32 v[64:65], s[10:11], v63, s20, 0
	v_lshl_add_u64 v[64:65], v[64:65], 2, v[4:5]
	global_load_dword v63, v[64:65], off nt
	s_and_b64 vcc, exec, s[4:5]
	s_cbranch_vccnz .LBB0_284
	global_load_dword v61, v[6:7], off offset:184
.LBB0_284:
	v_or_b32_e32 v64, 46, v2
	v_mad_i64_i32 v[64:65], s[10:11], v64, s20, 0
	v_lshl_add_u64 v[64:65], v[64:65], 2, v[4:5]
	global_load_dword v64, v[64:65], off nt
	v_mov_b32_e32 v65, 1.0
	s_and_b64 vcc, exec, s[4:5]
	v_mov_b32_e32 v66, 1.0
	s_cbranch_vccnz .LBB0_286
	global_load_dword v66, v[6:7], off offset:192
.LBB0_286:
	v_or_b32_e32 v67, 48, v2
	v_mad_i64_i32 v[68:69], s[10:11], v67, s20, 0
	v_lshl_add_u64 v[68:69], v[68:69], 2, v[4:5]
	global_load_dword v67, v[68:69], off nt
	s_and_b64 vcc, exec, s[4:5]
	s_cbranch_vccnz .LBB0_288
	global_load_dword v65, v[6:7], off offset:200
.LBB0_288:
	v_or_b32_e32 v68, 50, v2
	v_mad_i64_i32 v[68:69], s[10:11], v68, s20, 0
	v_lshl_add_u64 v[68:69], v[68:69], 2, v[4:5]
	global_load_dword v68, v[68:69], off nt
	v_mov_b32_e32 v69, 1.0
	s_and_b64 vcc, exec, s[4:5]
	v_mov_b32_e32 v70, 1.0
	s_cbranch_vccnz .LBB0_290
	global_load_dword v70, v[6:7], off offset:208
.LBB0_290:
	v_or_b32_e32 v71, 52, v2
	v_mad_i64_i32 v[72:73], s[10:11], v71, s20, 0
	v_lshl_add_u64 v[72:73], v[72:73], 2, v[4:5]
	global_load_dword v71, v[72:73], off nt
	s_and_b64 vcc, exec, s[4:5]
	s_cbranch_vccnz .LBB0_292
	global_load_dword v69, v[6:7], off offset:216
.LBB0_292:
	v_or_b32_e32 v72, 54, v2
	v_mad_i64_i32 v[72:73], s[10:11], v72, s20, 0
	v_lshl_add_u64 v[72:73], v[72:73], 2, v[4:5]
	global_load_dword v72, v[72:73], off nt
	v_mov_b32_e32 v73, 1.0
	s_and_b64 vcc, exec, s[4:5]
	v_mov_b32_e32 v74, 1.0
	s_cbranch_vccnz .LBB0_294
	global_load_dword v74, v[6:7], off offset:224
.LBB0_294:
	v_or_b32_e32 v75, 56, v2
	v_mad_i64_i32 v[76:77], s[10:11], v75, s20, 0
	v_lshl_add_u64 v[76:77], v[76:77], 2, v[4:5]
	global_load_dword v75, v[76:77], off nt
	s_and_b64 vcc, exec, s[4:5]
	s_cbranch_vccnz .LBB0_296
	global_load_dword v73, v[6:7], off offset:232
.LBB0_296:
	v_or_b32_e32 v76, 58, v2
	v_mad_i64_i32 v[76:77], s[10:11], v76, s20, 0
	v_lshl_add_u64 v[76:77], v[76:77], 2, v[4:5]
	global_load_dword v77, v[76:77], off nt
	v_mov_b32_e32 v76, 1.0
	s_and_b64 vcc, exec, s[4:5]
	v_mov_b32_e32 v78, 1.0
	s_cbranch_vccnz .LBB0_298
	global_load_dword v78, v[6:7], off offset:240
.LBB0_298:
	v_or_b32_e32 v79, 60, v2
	v_mad_i64_i32 v[80:81], s[10:11], v79, s20, 0
	v_lshl_add_u64 v[80:81], v[80:81], 2, v[4:5]
	global_load_dword v79, v[80:81], off nt
	s_and_b64 vcc, exec, s[4:5]
	s_cbranch_vccnz .LBB0_233
	global_load_dword v76, v[6:7], off offset:248
	s_branch .LBB0_233

.LBB0_333:
	v_or_b32_e32 v39, 28, v2
	v_mad_i64_i32 v[40:41], s[10:11], v39, s18, 0
	v_lshl_add_u64 v[40:41], v[40:41], 2, v[4:5]
	global_load_dword v39, v[40:41], off nt
	s_and_b64 vcc, exec, s[4:5]
	s_cbranch_vccnz .LBB0_335
	global_load_dword v34, v[6:7], off offset:120
.LBB0_335:
	v_or_b32_e32 v40, 30, v2
	v_mad_i64_i32 v[40:41], s[10:11], v40, s18, 0
	v_lshl_add_u64 v[40:41], v[40:41], 2, v[4:5]
	global_load_dword v40, v[40:41], off nt
	v_mov_b32_e32 v41, 1.0
	s_and_b64 vcc, exec, s[4:5]
	v_mov_b32_e32 v42, 1.0
	s_cbranch_vccnz .LBB0_337
	global_load_dword v42, v[6:7], off offset:128
.LBB0_337:
	v_or_b32_e32 v43, 32, v2
	v_mad_i64_i32 v[44:45], s[10:11], v43, s18, 0
	v_lshl_add_u64 v[44:45], v[44:45], 2, v[4:5]
	global_load_dword v43, v[44:45], off nt
	s_and_b64 vcc, exec, s[4:5]
	s_cbranch_vccnz .LBB0_339
	global_load_dword v41, v[6:7], off offset:136
.LBB0_339:
	v_or_b32_e32 v44, 34, v2
	v_mad_i64_i32 v[44:45], s[10:11], v44, s18, 0
	v_lshl_add_u64 v[44:45], v[44:45], 2, v[4:5]
	global_load_dword v44, v[44:45], off nt
	v_mov_b32_e32 v45, 1.0
	s_and_b64 vcc, exec, s[4:5]
	v_mov_b32_e32 v46, 1.0
	s_cbranch_vccnz .LBB0_341
	global_load_dword v46, v[6:7], off offset:144
.LBB0_341:
	v_or_b32_e32 v47, 36, v2
	v_mad_i64_i32 v[48:49], s[10:11], v47, s18, 0
	v_lshl_add_u64 v[48:49], v[48:49], 2, v[4:5]
	global_load_dword v47, v[48:49], off nt
	s_and_b64 vcc, exec, s[4:5]
	s_cbranch_vccnz .LBB0_343
	global_load_dword v45, v[6:7], off offset:152
.LBB0_343:
	v_or_b32_e32 v48, 38, v2
	v_mad_i64_i32 v[48:49], s[10:11], v48, s18, 0
	v_lshl_add_u64 v[48:49], v[48:49], 2, v[4:5]
	global_load_dword v48, v[48:49], off nt
	v_mov_b32_e32 v49, 1.0
	s_and_b64 vcc, exec, s[4:5]
	v_mov_b32_e32 v50, 1.0
	s_cbranch_vccnz .LBB0_345
	global_load_dword v50, v[6:7], off offset:160
.LBB0_345:
	v_or_b32_e32 v51, 40, v2
	v_mad_i64_i32 v[52:53], s[10:11], v51, s18, 0
	v_lshl_add_u64 v[52:53], v[52:53], 2, v[4:5]
	global_load_dword v51, v[52:53], off nt
	s_and_b64 vcc, exec, s[4:5]
	s_cbranch_vccnz .LBB0_347
	global_load_dword v49, v[6:7], off offset:168
.LBB0_347:
	v_or_b32_e32 v52, 42, v2
	v_mad_i64_i32 v[52:53], s[10:11], v52, s18, 0
	v_lshl_add_u64 v[52:53], v[52:53], 2, v[4:5]
	global_load_dword v52, v[52:53], off nt
	v_mov_b32_e32 v53, 1.0
	s_and_b64 vcc, exec, s[4:5]
	v_mov_b32_e32 v54, 1.0
	s_cbranch_vccnz .LBB0_349
	global_load_dword v54, v[6:7], off offset:176
.LBB0_349:
	v_or_b32_e32 v55, 44, v2
	v_mad_i64_i32 v[56:57], s[10:11], v55, s18, 0
	v_lshl_add_u64 v[56:57], v[56:57], 2, v[4:5]
	global_load_dword v55, v[56:57], off nt
	s_and_b64 vcc, exec, s[4:5]
	s_cbranch_vccnz .LBB0_351
	global_load_dword v53, v[6:7], off offset:184
.LBB0_351:
	v_or_b32_e32 v56, 46, v2
	v_mad_i64_i32 v[56:57], s[10:11], v56, s18, 0
	v_lshl_add_u64 v[56:57], v[56:57], 2, v[4:5]
	global_load_dword v56, v[56:57], off nt
	v_mov_b32_e32 v57, 1.0
	s_and_b64 vcc, exec, s[4:5]
	v_mov_b32_e32 v58, 1.0
	s_cbranch_vccnz .LBB0_353
	global_load_dword v58, v[6:7], off offset:192
.LBB0_353:
	v_or_b32_e32 v59, 48, v2
	v_mad_i64_i32 v[60:61], s[10:11], v59, s18, 0
	v_lshl_add_u64 v[60:61], v[60:61], 2, v[4:5]
	global_load_dword v59, v[60:61], off nt
	s_and_b64 vcc, exec, s[4:5]
	s_cbranch_vccnz .LBB0_355
	global_load_dword v57, v[6:7], off offset:200
.LBB0_355:
	v_or_b32_e32 v60, 50, v2
	v_mad_i64_i32 v[60:61], s[10:11], v60, s18, 0
	v_lshl_add_u64 v[60:61], v[60:61], 2, v[4:5]
	global_load_dword v60, v[60:61], off nt
	v_mov_b32_e32 v61, 1.0
	s_and_b64 vcc, exec, s[4:5]
	v_mov_b32_e32 v62, 1.0
	s_cbranch_vccnz .LBB0_357
	global_load_dword v62, v[6:7], off offset:208
.LBB0_357:
	v_or_b32_e32 v63, 52, v2
	v_mad_i64_i32 v[64:65], s[10:11], v63, s18, 0
	v_lshl_add_u64 v[64:65], v[64:65], 2, v[4:5]
	global_load_dword v63, v[64:65], off nt
	s_and_b64 vcc, exec, s[4:5]
	s_cbranch_vccnz .LBB0_359
	global_load_dword v61, v[6:7], off offset:216
.LBB0_359:
	v_or_b32_e32 v64, 54, v2
	v_mad_i64_i32 v[64:65], s[10:11], v64, s18, 0
	v_lshl_add_u64 v[64:65], v[64:65], 2, v[4:5]
	global_load_dword v64, v[64:65], off nt
	v_mov_b32_e32 v65, 1.0
	s_and_b64 vcc, exec, s[4:5]
	v_mov_b32_e32 v66, 1.0
	s_cbranch_vccnz .LBB0_361
	global_load_dword v66, v[6:7], off offset:224
.LBB0_361:
	v_or_b32_e32 v67, 56, v2
	v_mad_i64_i32 v[68:69], s[10:11], v67, s18, 0
	v_lshl_add_u64 v[68:69], v[68:69], 2, v[4:5]
	global_load_dword v67, v[68:69], off nt
	s_and_b64 vcc, exec, s[4:5]
	s_cbranch_vccnz .LBB0_363
	global_load_dword v65, v[6:7], off offset:232
.LBB0_363:
	v_or_b32_e32 v68, 58, v2
	v_mad_i64_i32 v[68:69], s[10:11], v68, s18, 0
	v_lshl_add_u64 v[68:69], v[68:69], 2, v[4:5]
	global_load_dword v69, v[68:69], off nt
	v_mov_b32_e32 v68, 1.0
	s_and_b64 vcc, exec, s[4:5]
	v_mov_b32_e32 v70, 1.0
	s_cbranch_vccnz .LBB0_365
	global_load_dword v70, v[6:7], off offset:240
.LBB0_365:
	v_or_b32_e32 v71, 60, v2
	v_mad_i64_i32 v[72:73], s[10:11], v71, s18, 0
	v_lshl_add_u64 v[72:73], v[72:73], 2, v[4:5]
	global_load_dword v71, v[72:73], off nt
	s_and_b64 vcc, exec, s[4:5]
	s_cbranch_vccnz .LBB0_367
	global_load_dword v68, v[6:7], off offset:248

.LBB0_375:
	s_xor_b64 s[10:11], s[10:11], -1
	s_and_b64 s[4:5], s[4:5], exec
	s_mul_i32 s22, s22, s20
	s_cselect_b32 s23, s17, s15
	s_cselect_b32 s24, s16, s14
	s_sub_i32 s4, s21, s22
	s_lshl_b32 s4, s4, 5
	s_ashr_i32 s5, s4, 31
	s_lshl_b64 s[4:5], s[4:5], 2
	s_add_u32 s4, s24, s4
	s_addc_u32 s5, s23, s5
	v_lshl_add_u64 v[4:5], s[4:5], 0, v[0:1]
	v_mad_i64_i32 v[10:11], s[4:5], v2, s19, 0
	v_lshl_add_u64 v[10:11], v[10:11], 2, v[4:5]
	global_load_dword v9, v[10:11], off nt
	v_cndmask_b32_e64 v10, 0, 1, s[10:11]
	v_cmp_ne_u32_e64 s[4:5], 1, v10
	s_andn2_b64 vcc, exec, s[10:11]
	s_cbranch_vccnz .LBB0_377
	global_load_dword v8, v[6:7], off offset:8
.LBB0_377:
	v_or_b32_e32 v10, 2, v2
	v_mad_i64_i32 v[10:11], s[10:11], v10, s19, 0
	v_lshl_add_u64 v[10:11], v[10:11], 2, v[4:5]
	global_load_dword v10, v[10:11], off nt
	v_mov_b32_e32 v11, 1.0
	s_and_b64 vcc, exec, s[4:5]
	v_mov_b32_e32 v12, 1.0
	s_cbranch_vccnz .LBB0_379
	global_load_dword v12, v[6:7], off offset:16
.LBB0_379:
	v_or_b32_e32 v13, 4, v2
	v_mad_i64_i32 v[14:15], s[10:11], v13, s19, 0
	v_lshl_add_u64 v[14:15], v[14:15], 2, v[4:5]
	global_load_dword v13, v[14:15], off nt
	s_and_b64 vcc, exec, s[4:5]
	s_cbranch_vccnz .LBB0_381
	global_load_dword v11, v[6:7], off offset:24
.LBB0_381:
	v_or_b32_e32 v14, 6, v2
	v_mad_i64_i32 v[14:15], s[10:11], v14, s19, 0
	v_lshl_add_u64 v[14:15], v[14:15], 2, v[4:5]
	global_load_dword v14, v[14:15], off nt
	v_mov_b32_e32 v15, 1.0
	s_and_b64 vcc, exec, s[4:5]
	v_mov_b32_e32 v16, 1.0
	s_cbranch_vccnz .LBB0_383
	global_load_dword v16, v[6:7], off offset:32
.LBB0_383:
	v_or_b32_e32 v17, 8, v2
	v_mad_i64_i32 v[18:19], s[10:11], v17, s19, 0
	v_lshl_add_u64 v[18:19], v[18:19], 2, v[4:5]
	global_load_dword v17, v[18:19], off nt
	s_and_b64 vcc, exec, s[4:5]
	s_cbranch_vccnz .LBB0_385
	global_load_dword v15, v[6:7], off offset:40
.LBB0_385:
	v_or_b32_e32 v18, 10, v2
	v_mad_i64_i32 v[18:19], s[10:11], v18, s19, 0
	v_lshl_add_u64 v[18:19], v[18:19], 2, v[4:5]
	global_load_dword v18, v[18:19], off nt
	v_mov_b32_e32 v19, 1.0
	s_and_b64 vcc, exec, s[4:5]
	v_mov_b32_e32 v20, 1.0
	s_cbranch_vccnz .LBB0_387
	global_load_dword v20, v[6:7], off offset:48
.LBB0_387:
	v_or_b32_e32 v21, 12, v2
	v_mad_i64_i32 v[22:23], s[10:11], v21, s19, 0
	v_lshl_add_u64 v[22:23], v[22:23], 2, v[4:5]
	global_load_dword v21, v[22:23], off nt
	s_and_b64 vcc, exec, s[4:5]
	s_cbranch_vccnz .LBB0_389
	global_load_dword v19, v[6:7], off offset:56
.LBB0_389:
	v_or_b32_e32 v22, 14, v2
	v_mad_i64_i32 v[22:23], s[10:11], v22, s19, 0
	v_lshl_add_u64 v[22:23], v[22:23], 2, v[4:5]
	global_load_dword v22, v[22:23], off nt
	v_mov_b32_e32 v23, 1.0
	s_and_b64 vcc, exec, s[4:5]
	v_mov_b32_e32 v24, 1.0
	s_cbranch_vccnz .LBB0_391
	global_load_dword v24, v[6:7], off offset:64
.LBB0_391:
	v_or_b32_e32 v25, 16, v2
	v_mad_i64_i32 v[26:27], s[10:11], v25, s19, 0
	v_lshl_add_u64 v[26:27], v[26:27], 2, v[4:5]
	global_load_dword v25, v[26:27], off nt
	s_and_b64 vcc, exec, s[4:5]
	s_cbranch_vccnz .LBB0_393
	global_load_dword v23, v[6:7], off offset:72
.LBB0_393:
	v_or_b32_e32 v26, 18, v2
	v_mad_i64_i32 v[26:27], s[10:11], v26, s19, 0
	v_lshl_add_u64 v[26:27], v[26:27], 2, v[4:5]
	global_load_dword v26, v[26:27], off nt
	v_mov_b32_e32 v27, 1.0
	s_and_b64 vcc, exec, s[4:5]
	v_mov_b32_e32 v28, 1.0
	s_cbranch_vccnz .LBB0_395
	global_load_dword v28, v[6:7], off offset:80
.LBB0_395:
	v_or_b32_e32 v29, 20, v2
	v_mad_i64_i32 v[30:31], s[10:11], v29, s19, 0
	v_lshl_add_u64 v[30:31], v[30:31], 2, v[4:5]
	global_load_dword v29, v[30:31], off nt
	s_and_b64 vcc, exec, s[4:5]
	s_cbranch_vccnz .LBB0_397
	global_load_dword v27, v[6:7], off offset:88
.LBB0_397:
	v_or_b32_e32 v30, 22, v2
	v_mad_i64_i32 v[30:31], s[10:11], v30, s19, 0
	v_lshl_add_u64 v[30:31], v[30:31], 2, v[4:5]
	global_load_dword v30, v[30:31], off nt
	v_mov_b32_e32 v31, 1.0
	s_and_b64 vcc, exec, s[4:5]
	v_mov_b32_e32 v32, 1.0
	s_cbranch_vccnz .LBB0_399
	global_load_dword v32, v[6:7], off offset:96
.LBB0_399:
	v_or_b32_e32 v33, 24, v2
	v_mad_i64_i32 v[44:45], s[10:11], v33, s19, 0
	v_lshl_add_u64 v[44:45], v[44:45], 2, v[4:5]
	global_load_dword v33, v[44:45], off nt
	s_and_b64 vcc, exec, s[4:5]
	s_cbranch_vccnz .LBB0_401
	global_load_dword v31, v[6:7], off offset:104
.LBB0_401:
	v_or_b32_e32 v35, 26, v2
	v_mad_i64_i32 v[44:45], s[10:11], v35, s19, 0
	v_lshl_add_u64 v[44:45], v[44:45], 2, v[4:5]
	global_load_dword v35, v[44:45], off nt
	v_mov_b32_e32 v44, 1.0
	s_and_b64 vcc, exec, s[4:5]
	v_mov_b32_e32 v45, 1.0
	s_cbranch_vccnz .LBB0_403
	global_load_dword v45, v[6:7], off offset:112
.LBB0_403:
	v_or_b32_e32 v46, 28, v2
	v_mad_i64_i32 v[46:47], s[10:11], v46, s19, 0
	v_lshl_add_u64 v[46:47], v[46:47], 2, v[4:5]
	global_load_dword v46, v[46:47], off nt
	s_and_b64 vcc, exec, s[4:5]
	s_cbranch_vccnz .LBB0_405
	global_load_dword v44, v[6:7], off offset:120
.LBB0_405:
	v_or_b32_e32 v47, 30, v2
	v_mad_i64_i32 v[48:49], s[10:11], v47, s19, 0
	v_lshl_add_u64 v[48:49], v[48:49], 2, v[4:5]
	global_load_dword v47, v[48:49], off nt
	v_mov_b32_e32 v48, 1.0
	s_and_b64 vcc, exec, s[4:5]
	v_mov_b32_e32 v49, 1.0
	s_cbranch_vccnz .LBB0_407
	global_load_dword v49, v[6:7], off offset:128
.LBB0_407:
	v_or_b32_e32 v50, 32, v2
	v_mad_i64_i32 v[50:51], s[10:11], v50, s19, 0
	v_lshl_add_u64 v[50:51], v[50:51], 2, v[4:5]
	global_load_dword v50, v[50:51], off nt
	s_and_b64 vcc, exec, s[4:5]
	s_cbranch_vccnz .LBB0_409
	global_load_dword v48, v[6:7], off offset:136
.LBB0_409:
	v_or_b32_e32 v51, 34, v2
	v_mad_i64_i32 v[52:53], s[10:11], v51, s19, 0
	v_lshl_add_u64 v[52:53], v[52:53], 2, v[4:5]
	global_load_dword v51, v[52:53], off nt
	v_mov_b32_e32 v52, 1.0
	s_and_b64 vcc, exec, s[4:5]
	v_mov_b32_e32 v53, 1.0
	s_cbranch_vccnz .LBB0_411
	global_load_dword v53, v[6:7], off offset:144
.LBB0_411:
	v_or_b32_e32 v54, 36, v2
	v_mad_i64_i32 v[54:55], s[10:11], v54, s19, 0
	v_lshl_add_u64 v[54:55], v[54:55], 2, v[4:5]
	global_load_dword v54, v[54:55], off nt
	s_and_b64 vcc, exec, s[4:5]
	s_cbranch_vccnz .LBB0_413
	global_load_dword v52, v[6:7], off offset:152
.LBB0_413:
	v_or_b32_e32 v55, 38, v2
	v_mad_i64_i32 v[56:57], s[10:11], v55, s19, 0
	v_lshl_add_u64 v[56:57], v[56:57], 2, v[4:5]
	global_load_dword v55, v[56:57], off nt
	v_mov_b32_e32 v56, 1.0
	s_and_b64 vcc, exec, s[4:5]
	v_mov_b32_e32 v57, 1.0
	s_cbranch_vccnz .LBB0_415
	global_load_dword v57, v[6:7], off offset:160
.LBB0_415:
	v_or_b32_e32 v58, 40, v2
	v_mad_i64_i32 v[58:59], s[10:11], v58, s19, 0
	v_lshl_add_u64 v[58:59], v[58:59], 2, v[4:5]
	global_load_dword v58, v[58:59], off nt
	s_and_b64 vcc, exec, s[4:5]
	s_cbranch_vccnz .LBB0_417
	global_load_dword v56, v[6:7], off offset:168
.LBB0_417:
	v_or_b32_e32 v59, 42, v2
	v_mad_i64_i32 v[60:61], s[10:11], v59, s19, 0
	v_lshl_add_u64 v[60:61], v[60:61], 2, v[4:5]
	global_load_dword v59, v[60:61], off nt
	v_mov_b32_e32 v60, 1.0
	s_and_b64 vcc, exec, s[4:5]
	v_mov_b32_e32 v61, 1.0
	s_cbranch_vccnz .LBB0_419
	global_load_dword v61, v[6:7], off offset:176
.LBB0_419:
	v_or_b32_e32 v62, 44, v2
	v_mad_i64_i32 v[62:63], s[10:11], v62, s19, 0
	v_lshl_add_u64 v[62:63], v[62:63], 2, v[4:5]
	global_load_dword v62, v[62:63], off nt
	s_and_b64 vcc, exec, s[4:5]
	s_cbranch_vccnz .LBB0_421
	global_load_dword v60, v[6:7], off offset:184
.LBB0_421:
	v_or_b32_e32 v63, 46, v2
	v_mad_i64_i32 v[64:65], s[10:11], v63, s19, 0
	v_lshl_add_u64 v[64:65], v[64:65], 2, v[4:5]
	global_load_dword v63, v[64:65], off nt
	v_mov_b32_e32 v64, 1.0
	s_and_b64 vcc, exec, s[4:5]
	v_mov_b32_e32 v65, 1.0
	s_cbranch_vccnz .LBB0_423
	global_load_dword v65, v[6:7], off offset:192
.LBB0_423:
	v_or_b32_e32 v66, 48, v2
	v_mad_i64_i32 v[66:67], s[10:11], v66, s19, 0
	v_lshl_add_u64 v[66:67], v[66:67], 2, v[4:5]
	global_load_dword v66, v[66:67], off nt
	s_and_b64 vcc, exec, s[4:5]
	s_cbranch_vccnz .LBB0_425
	global_load_dword v64, v[6:7], off offset:200
.LBB0_425:
	v_or_b32_e32 v67, 50, v2
	v_mad_i64_i32 v[68:69], s[10:11], v67, s19, 0
	v_lshl_add_u64 v[68:69], v[68:69], 2, v[4:5]
	global_load_dword v67, v[68:69], off nt
	v_mov_b32_e32 v68, 1.0
	s_and_b64 vcc, exec, s[4:5]
	v_mov_b32_e32 v69, 1.0
	s_cbranch_vccnz .LBB0_427
	global_load_dword v69, v[6:7], off offset:208
.LBB0_427:
	v_or_b32_e32 v70, 52, v2
	v_mad_i64_i32 v[70:71], s[10:11], v70, s19, 0
	v_lshl_add_u64 v[70:71], v[70:71], 2, v[4:5]
	global_load_dword v70, v[70:71], off nt
	s_and_b64 vcc, exec, s[4:5]
	s_cbranch_vccnz .LBB0_429
	global_load_dword v68, v[6:7], off offset:216
.LBB0_429:
	v_or_b32_e32 v71, 54, v2
	v_mad_i64_i32 v[72:73], s[10:11], v71, s19, 0
	v_lshl_add_u64 v[72:73], v[72:73], 2, v[4:5]
	global_load_dword v71, v[72:73], off nt
	v_mov_b32_e32 v72, 1.0
	s_and_b64 vcc, exec, s[4:5]
	v_mov_b32_e32 v73, 1.0
	s_cbranch_vccnz .LBB0_431
	global_load_dword v73, v[6:7], off offset:224
.LBB0_431:
	v_or_b32_e32 v74, 56, v2
	v_mad_i64_i32 v[74:75], s[10:11], v74, s19, 0
	v_lshl_add_u64 v[74:75], v[74:75], 2, v[4:5]
	global_load_dword v74, v[74:75], off nt
	s_and_b64 vcc, exec, s[4:5]
	s_cbranch_vccnz .LBB0_433
	global_load_dword v72, v[6:7], off offset:232
.LBB0_433:
	v_or_b32_e32 v75, 58, v2
	v_mad_i64_i32 v[76:77], s[10:11], v75, s19, 0
	v_lshl_add_u64 v[76:77], v[76:77], 2, v[4:5]
	global_load_dword v76, v[76:77], off nt
	v_mov_b32_e32 v75, 1.0
	s_and_b64 vcc, exec, s[4:5]
	v_mov_b32_e32 v77, 1.0
	s_cbranch_vccnz .LBB0_435
	global_load_dword v77, v[6:7], off offset:240
.LBB0_435:
	v_or_b32_e32 v78, 60, v2
	v_mad_i64_i32 v[78:79], s[10:11], v78, s19, 0
	v_lshl_add_u64 v[78:79], v[78:79], 2, v[4:5]
	global_load_dword v78, v[78:79], off nt
	s_and_b64 vcc, exec, s[4:5]
	s_cbranch_vccnz .LBB0_370
	global_load_dword v75, v[6:7], off offset:248
	s_branch .LBB0_370

.LBB0_546:
	s_xor_b64 s[12:13], s[12:13], -1
	s_and_b64 s[4:5], s[4:5], exec
	s_mul_i32 s23, s23, s21
	s_cselect_b32 s24, s17, s15
	s_cselect_b32 s25, s16, s14
	s_sub_i32 s4, s22, s23
	s_lshl_b32 s4, s4, 5
	s_ashr_i32 s5, s4, 31
	s_lshl_b64 s[4:5], s[4:5], 2
	v_and_b32_e32 v0, 31, v35
	s_add_u32 s4, s25, s4
	s_addc_u32 s5, s24, s5
	v_lshlrev_b32_e32 v0, 2, v0
	v_lshl_add_u64 v[4:5], s[4:5], 0, v[0:1]
	v_mad_i64_i32 v[10:11], s[4:5], v2, s20, 0
	v_lshl_add_u64 v[10:11], v[10:11], 2, v[4:5]
	global_load_dword v0, v[10:11], off nt
	v_cndmask_b32_e64 v9, 0, 1, s[12:13]
	v_cmp_ne_u32_e64 s[4:5], 1, v9
	s_andn2_b64 vcc, exec, s[12:13]
	s_cbranch_vccnz .LBB0_548
	global_load_dword v8, v[6:7], off offset:8
.LBB0_548:
	v_or_b32_e32 v9, 2, v2
	v_mad_i64_i32 v[10:11], s[12:13], v9, s20, 0
	v_lshl_add_u64 v[10:11], v[10:11], 2, v[4:5]
	global_load_dword v9, v[10:11], off nt
	v_mov_b32_e32 v10, 1.0
	s_and_b64 vcc, exec, s[4:5]
	v_mov_b32_e32 v11, 1.0
	s_cbranch_vccnz .LBB0_550
	global_load_dword v11, v[6:7], off offset:16
.LBB0_550:
	v_or_b32_e32 v12, 4, v2
	v_mad_i64_i32 v[12:13], s[12:13], v12, s20, 0
	v_lshl_add_u64 v[12:13], v[12:13], 2, v[4:5]
	global_load_dword v12, v[12:13], off nt
	s_and_b64 vcc, exec, s[4:5]
	s_cbranch_vccnz .LBB0_552
	global_load_dword v10, v[6:7], off offset:24
.LBB0_552:
	v_or_b32_e32 v13, 6, v2
	v_mad_i64_i32 v[14:15], s[12:13], v13, s20, 0
	v_lshl_add_u64 v[14:15], v[14:15], 2, v[4:5]
	global_load_dword v13, v[14:15], off nt
	v_mov_b32_e32 v14, 1.0
	s_and_b64 vcc, exec, s[4:5]
	v_mov_b32_e32 v15, 1.0
	s_cbranch_vccnz .LBB0_554
	global_load_dword v15, v[6:7], off offset:32
.LBB0_554:
	v_or_b32_e32 v16, 8, v2
	v_mad_i64_i32 v[16:17], s[12:13], v16, s20, 0
	v_lshl_add_u64 v[16:17], v[16:17], 2, v[4:5]
	global_load_dword v16, v[16:17], off nt
	s_and_b64 vcc, exec, s[4:5]
	s_cbranch_vccnz .LBB0_556
	global_load_dword v14, v[6:7], off offset:40
.LBB0_556:
	v_or_b32_e32 v17, 10, v2
	v_mad_i64_i32 v[18:19], s[12:13], v17, s20, 0
	v_lshl_add_u64 v[18:19], v[18:19], 2, v[4:5]
	global_load_dword v17, v[18:19], off nt
	v_mov_b32_e32 v18, 1.0
	s_and_b64 vcc, exec, s[4:5]
	v_mov_b32_e32 v19, 1.0
	s_cbranch_vccnz .LBB0_558
	global_load_dword v19, v[6:7], off offset:48
.LBB0_558:
	v_or_b32_e32 v20, 12, v2
	v_mad_i64_i32 v[20:21], s[12:13], v20, s20, 0
	v_lshl_add_u64 v[20:21], v[20:21], 2, v[4:5]
	global_load_dword v20, v[20:21], off nt
	s_and_b64 vcc, exec, s[4:5]
	s_cbranch_vccnz .LBB0_560
	global_load_dword v18, v[6:7], off offset:56
.LBB0_560:
	v_or_b32_e32 v21, 14, v2
	v_mad_i64_i32 v[22:23], s[12:13], v21, s20, 0
	v_lshl_add_u64 v[22:23], v[22:23], 2, v[4:5]
	global_load_dword v21, v[22:23], off nt
	v_mov_b32_e32 v22, 1.0
	s_and_b64 vcc, exec, s[4:5]
	v_mov_b32_e32 v23, 1.0
	s_cbranch_vccnz .LBB0_562
	global_load_dword v23, v[6:7], off offset:64
.LBB0_562:
	v_or_b32_e32 v24, 16, v2
	v_mad_i64_i32 v[24:25], s[12:13], v24, s20, 0
	v_lshl_add_u64 v[24:25], v[24:25], 2, v[4:5]
	global_load_dword v24, v[24:25], off nt
	s_and_b64 vcc, exec, s[4:5]
	s_cbranch_vccnz .LBB0_564
	global_load_dword v22, v[6:7], off offset:72
.LBB0_564:
	v_or_b32_e32 v25, 18, v2
	v_mad_i64_i32 v[26:27], s[12:13], v25, s20, 0
	v_lshl_add_u64 v[26:27], v[26:27], 2, v[4:5]
	global_load_dword v25, v[26:27], off nt
	v_mov_b32_e32 v26, 1.0
	s_and_b64 vcc, exec, s[4:5]
	v_mov_b32_e32 v27, 1.0
	s_cbranch_vccnz .LBB0_566
	global_load_dword v27, v[6:7], off offset:80
.LBB0_566:
	v_or_b32_e32 v28, 20, v2
	v_mad_i64_i32 v[28:29], s[12:13], v28, s20, 0
	v_lshl_add_u64 v[28:29], v[28:29], 2, v[4:5]
	global_load_dword v28, v[28:29], off nt
	s_and_b64 vcc, exec, s[4:5]
	s_cbranch_vccnz .LBB0_568
	global_load_dword v26, v[6:7], off offset:88
.LBB0_568:
	v_or_b32_e32 v29, 22, v2
	v_mad_i64_i32 v[30:31], s[12:13], v29, s20, 0
	v_lshl_add_u64 v[30:31], v[30:31], 2, v[4:5]
	global_load_dword v29, v[30:31], off nt
	v_mov_b32_e32 v30, 1.0
	s_and_b64 vcc, exec, s[4:5]
	v_mov_b32_e32 v31, 1.0
	s_cbranch_vccnz .LBB0_570
	global_load_dword v31, v[6:7], off offset:96
.LBB0_570:
	v_or_b32_e32 v32, 24, v2
	v_mad_i64_i32 v[32:33], s[12:13], v32, s20, 0
	v_lshl_add_u64 v[32:33], v[32:33], 2, v[4:5]
	global_load_dword v32, v[32:33], off nt
	s_and_b64 vcc, exec, s[4:5]
	s_cbranch_vccnz .LBB0_572
	global_load_dword v30, v[6:7], off offset:104
.LBB0_572:
	v_or_b32_e32 v33, 26, v2
	v_mad_i64_i32 v[38:39], s[12:13], v33, s20, 0
	v_lshl_add_u64 v[38:39], v[38:39], 2, v[4:5]
	global_load_dword v33, v[38:39], off nt
	v_mov_b32_e32 v37, 1.0
	s_and_b64 vcc, exec, s[4:5]
	v_mov_b32_e32 v38, 1.0
	s_cbranch_vccnz .LBB0_574
	global_load_dword v38, v[6:7], off offset:112
.LBB0_574:
	v_or_b32_e32 v39, 28, v2
	v_mad_i64_i32 v[40:41], s[12:13], v39, s20, 0
	v_lshl_add_u64 v[40:41], v[40:41], 2, v[4:5]
	global_load_dword v39, v[40:41], off nt
	s_and_b64 vcc, exec, s[4:5]
	s_cbranch_vccnz .LBB0_576
	global_load_dword v37, v[6:7], off offset:120
.LBB0_576:
	v_or_b32_e32 v40, 30, v2
	v_mad_i64_i32 v[40:41], s[12:13], v40, s20, 0
	v_lshl_add_u64 v[40:41], v[40:41], 2, v[4:5]
	global_load_dword v40, v[40:41], off nt
	v_mov_b32_e32 v41, 1.0
	s_and_b64 vcc, exec, s[4:5]
	v_mov_b32_e32 v42, 1.0
	s_cbranch_vccnz .LBB0_578
	global_load_dword v42, v[6:7], off offset:128
.LBB0_578:
	v_or_b32_e32 v43, 32, v2
	v_mad_i64_i32 v[44:45], s[12:13], v43, s20, 0
	v_lshl_add_u64 v[44:45], v[44:45], 2, v[4:5]
	global_load_dword v43, v[44:45], off nt
	s_and_b64 vcc, exec, s[4:5]
	s_cbranch_vccnz .LBB0_580
	global_load_dword v41, v[6:7], off offset:136
.LBB0_580:
	v_or_b32_e32 v44, 34, v2
	v_mad_i64_i32 v[44:45], s[12:13], v44, s20, 0
	v_lshl_add_u64 v[44:45], v[44:45], 2, v[4:5]
	global_load_dword v44, v[44:45], off nt
	v_mov_b32_e32 v45, 1.0
	s_and_b64 vcc, exec, s[4:5]
	v_mov_b32_e32 v46, 1.0
	s_cbranch_vccnz .LBB0_582
	global_load_dword v46, v[6:7], off offset:144
.LBB0_582:
	v_or_b32_e32 v47, 36, v2
	v_mad_i64_i32 v[48:49], s[12:13], v47, s20, 0
	v_lshl_add_u64 v[48:49], v[48:49], 2, v[4:5]
	global_load_dword v47, v[48:49], off nt
	s_and_b64 vcc, exec, s[4:5]
	s_cbranch_vccnz .LBB0_584
	global_load_dword v45, v[6:7], off offset:152
.LBB0_584:
	v_or_b32_e32 v48, 38, v2
	v_mad_i64_i32 v[48:49], s[12:13], v48, s20, 0
	v_lshl_add_u64 v[48:49], v[48:49], 2, v[4:5]
	global_load_dword v48, v[48:49], off nt
	v_mov_b32_e32 v49, 1.0
	s_and_b64 vcc, exec, s[4:5]
	v_mov_b32_e32 v50, 1.0
	s_cbranch_vccnz .LBB0_586
	global_load_dword v50, v[6:7], off offset:160
.LBB0_586:
	v_or_b32_e32 v51, 40, v2
	v_mad_i64_i32 v[52:53], s[12:13], v51, s20, 0
	v_lshl_add_u64 v[52:53], v[52:53], 2, v[4:5]
	global_load_dword v51, v[52:53], off nt
	s_and_b64 vcc, exec, s[4:5]
	s_cbranch_vccnz .LBB0_588
	global_load_dword v49, v[6:7], off offset:168
.LBB0_588:
	v_or_b32_e32 v52, 42, v2
	v_mad_i64_i32 v[52:53], s[12:13], v52, s20, 0
	v_lshl_add_u64 v[52:53], v[52:53], 2, v[4:5]
	global_load_dword v52, v[52:53], off nt
	v_mov_b32_e32 v53, 1.0
	s_and_b64 vcc, exec, s[4:5]
	v_mov_b32_e32 v54, 1.0
	s_cbranch_vccnz .LBB0_590
	global_load_dword v54, v[6:7], off offset:176
.LBB0_590:
	v_or_b32_e32 v55, 44, v2
	v_mad_i64_i32 v[56:57], s[12:13], v55, s20, 0
	v_lshl_add_u64 v[56:57], v[56:57], 2, v[4:5]
	global_load_dword v55, v[56:57], off nt
	s_and_b64 vcc, exec, s[4:5]
	s_cbranch_vccnz .LBB0_592
	global_load_dword v53, v[6:7], off offset:184
.LBB0_592:
	v_or_b32_e32 v56, 46, v2
	v_mad_i64_i32 v[56:57], s[12:13], v56, s20, 0
	v_lshl_add_u64 v[56:57], v[56:57], 2, v[4:5]
	global_load_dword v56, v[56:57], off nt
	v_mov_b32_e32 v57, 1.0
	s_and_b64 vcc, exec, s[4:5]
	v_mov_b32_e32 v58, 1.0
	s_cbranch_vccnz .LBB0_594
	global_load_dword v58, v[6:7], off offset:192
.LBB0_594:
	v_or_b32_e32 v59, 48, v2
	v_mad_i64_i32 v[60:61], s[12:13], v59, s20, 0
	v_lshl_add_u64 v[60:61], v[60:61], 2, v[4:5]
	global_load_dword v59, v[60:61], off nt
	s_and_b64 vcc, exec, s[4:5]
	s_cbranch_vccnz .LBB0_596
	global_load_dword v57, v[6:7], off offset:200
.LBB0_596:
	v_or_b32_e32 v60, 50, v2
	v_mad_i64_i32 v[60:61], s[12:13], v60, s20, 0
	v_lshl_add_u64 v[60:61], v[60:61], 2, v[4:5]
	global_load_dword v60, v[60:61], off nt
	v_mov_b32_e32 v61, 1.0
	s_and_b64 vcc, exec, s[4:5]
	v_mov_b32_e32 v62, 1.0
	s_cbranch_vccnz .LBB0_598
	global_load_dword v62, v[6:7], off offset:208
.LBB0_598:
	v_or_b32_e32 v63, 52, v2
	v_mad_i64_i32 v[64:65], s[12:13], v63, s20, 0
	v_lshl_add_u64 v[64:65], v[64:65], 2, v[4:5]
	global_load_dword v63, v[64:65], off nt
	s_and_b64 vcc, exec, s[4:5]
	s_cbranch_vccnz .LBB0_600
	global_load_dword v61, v[6:7], off offset:216
.LBB0_600:
	v_or_b32_e32 v64, 54, v2
	v_mad_i64_i32 v[64:65], s[12:13], v64, s20, 0
	v_lshl_add_u64 v[64:65], v[64:65], 2, v[4:5]
	global_load_dword v64, v[64:65], off nt
	v_mov_b32_e32 v65, 1.0
	s_and_b64 vcc, exec, s[4:5]
	v_mov_b32_e32 v66, 1.0
	s_cbranch_vccnz .LBB0_602
	global_load_dword v66, v[6:7], off offset:224
.LBB0_602:
	v_or_b32_e32 v67, 56, v2
	v_mad_i64_i32 v[68:69], s[12:13], v67, s20, 0
	v_lshl_add_u64 v[68:69], v[68:69], 2, v[4:5]
	global_load_dword v67, v[68:69], off nt
	s_and_b64 vcc, exec, s[4:5]
	s_cbranch_vccnz .LBB0_604
	global_load_dword v65, v[6:7], off offset:232
.LBB0_604:
	v_or_b32_e32 v68, 58, v2
	v_mad_i64_i32 v[68:69], s[12:13], v68, s20, 0
	v_lshl_add_u64 v[68:69], v[68:69], 2, v[4:5]
	global_load_dword v69, v[68:69], off nt
	v_mov_b32_e32 v68, 1.0
	s_and_b64 vcc, exec, s[4:5]
	v_mov_b32_e32 v70, 1.0
	s_cbranch_vccnz .LBB0_606
	global_load_dword v70, v[6:7], off offset:240
.LBB0_606:
	v_or_b32_e32 v71, 60, v2
	v_mad_i64_i32 v[72:73], s[12:13], v71, s20, 0
	v_lshl_add_u64 v[72:73], v[72:73], 2, v[4:5]
	global_load_dword v71, v[72:73], off nt
	s_and_b64 vcc, exec, s[4:5]
	s_cbranch_vccnz .LBB0_608
	global_load_dword v68, v[6:7], off offset:248

.LBB0_615:
	s_xor_b64 s[12:13], s[12:13], -1
	s_and_b64 s[4:5], s[4:5], exec
	s_mul_i32 s23, s23, s21
	s_cselect_b32 s24, s17, s15
	s_cselect_b32 s25, s16, s14
	s_sub_i32 s4, s22, s23
	s_lshl_b32 s4, s4, 5
	s_ashr_i32 s5, s4, 31
	s_lshl_b64 s[4:5], s[4:5], 2
	s_add_u32 s4, s25, s4
	s_addc_u32 s5, s24, s5
	v_lshl_add_u64 v[4:5], s[4:5], 0, v[0:1]
	v_mad_i64_i32 v[10:11], s[4:5], v2, s20, 0
	v_lshl_add_u64 v[10:11], v[10:11], 2, v[4:5]
	global_load_dword v9, v[10:11], off nt
	v_cndmask_b32_e64 v10, 0, 1, s[12:13]
	v_cmp_ne_u32_e64 s[4:5], 1, v10
	s_andn2_b64 vcc, exec, s[12:13]
	s_cbranch_vccnz .LBB0_617
	global_load_dword v8, v[6:7], off offset:8
.LBB0_617:
	v_or_b32_e32 v10, 2, v2
	v_mad_i64_i32 v[10:11], s[12:13], v10, s20, 0
	v_lshl_add_u64 v[10:11], v[10:11], 2, v[4:5]
	global_load_dword v10, v[10:11], off nt
	v_mov_b32_e32 v11, 1.0
	s_and_b64 vcc, exec, s[4:5]
	v_mov_b32_e32 v12, 1.0
	s_cbranch_vccnz .LBB0_619
	global_load_dword v12, v[6:7], off offset:16
.LBB0_619:
	v_or_b32_e32 v13, 4, v2
	v_mad_i64_i32 v[14:15], s[12:13], v13, s20, 0
	v_lshl_add_u64 v[14:15], v[14:15], 2, v[4:5]
	global_load_dword v13, v[14:15], off nt
	s_and_b64 vcc, exec, s[4:5]
	s_cbranch_vccnz .LBB0_621
	global_load_dword v11, v[6:7], off offset:24
.LBB0_621:
	v_or_b32_e32 v14, 6, v2
	v_mad_i64_i32 v[14:15], s[12:13], v14, s20, 0
	v_lshl_add_u64 v[14:15], v[14:15], 2, v[4:5]
	global_load_dword v14, v[14:15], off nt
	v_mov_b32_e32 v15, 1.0
	s_and_b64 vcc, exec, s[4:5]
	v_mov_b32_e32 v16, 1.0
	s_cbranch_vccnz .LBB0_623
	global_load_dword v16, v[6:7], off offset:32
.LBB0_623:
	v_or_b32_e32 v17, 8, v2
	v_mad_i64_i32 v[18:19], s[12:13], v17, s20, 0
	v_lshl_add_u64 v[18:19], v[18:19], 2, v[4:5]
	global_load_dword v17, v[18:19], off nt
	s_and_b64 vcc, exec, s[4:5]
	s_cbranch_vccnz .LBB0_625
	global_load_dword v15, v[6:7], off offset:40
.LBB0_625:
	v_or_b32_e32 v18, 10, v2
	v_mad_i64_i32 v[18:19], s[12:13], v18, s20, 0
	v_lshl_add_u64 v[18:19], v[18:19], 2, v[4:5]
	global_load_dword v18, v[18:19], off nt
	v_mov_b32_e32 v19, 1.0
	s_and_b64 vcc, exec, s[4:5]
	v_mov_b32_e32 v20, 1.0
	s_cbranch_vccnz .LBB0_627
	global_load_dword v20, v[6:7], off offset:48
.LBB0_627:
	v_or_b32_e32 v21, 12, v2
	v_mad_i64_i32 v[22:23], s[12:13], v21, s20, 0
	v_lshl_add_u64 v[22:23], v[22:23], 2, v[4:5]
	global_load_dword v21, v[22:23], off nt
	s_and_b64 vcc, exec, s[4:5]
	s_cbranch_vccnz .LBB0_629
	global_load_dword v19, v[6:7], off offset:56
.LBB0_629:
	v_or_b32_e32 v22, 14, v2
	v_mad_i64_i32 v[22:23], s[12:13], v22, s20, 0
	v_lshl_add_u64 v[22:23], v[22:23], 2, v[4:5]
	global_load_dword v22, v[22:23], off nt
	v_mov_b32_e32 v23, 1.0
	s_and_b64 vcc, exec, s[4:5]
	v_mov_b32_e32 v24, 1.0
	s_cbranch_vccnz .LBB0_631
	global_load_dword v24, v[6:7], off offset:64
.LBB0_631:
	v_or_b32_e32 v25, 16, v2
	v_mad_i64_i32 v[26:27], s[12:13], v25, s20, 0
	v_lshl_add_u64 v[26:27], v[26:27], 2, v[4:5]
	global_load_dword v25, v[26:27], off nt
	s_and_b64 vcc, exec, s[4:5]
	s_cbranch_vccnz .LBB0_633
	global_load_dword v23, v[6:7], off offset:72
.LBB0_633:
	v_or_b32_e32 v26, 18, v2
	v_mad_i64_i32 v[26:27], s[12:13], v26, s20, 0
	v_lshl_add_u64 v[26:27], v[26:27], 2, v[4:5]
	global_load_dword v26, v[26:27], off nt
	v_mov_b32_e32 v27, 1.0
	s_and_b64 vcc, exec, s[4:5]
	v_mov_b32_e32 v28, 1.0
	s_cbranch_vccnz .LBB0_635
	global_load_dword v28, v[6:7], off offset:80
.LBB0_635:
	v_or_b32_e32 v29, 20, v2
	v_mad_i64_i32 v[30:31], s[12:13], v29, s20, 0
	v_lshl_add_u64 v[30:31], v[30:31], 2, v[4:5]
	global_load_dword v29, v[30:31], off nt
	s_and_b64 vcc, exec, s[4:5]
	s_cbranch_vccnz .LBB0_637
	global_load_dword v27, v[6:7], off offset:88
.LBB0_637:
	v_or_b32_e32 v30, 22, v2
	v_mad_i64_i32 v[30:31], s[12:13], v30, s20, 0
	v_lshl_add_u64 v[30:31], v[30:31], 2, v[4:5]
	global_load_dword v30, v[30:31], off nt
	v_mov_b32_e32 v31, 1.0
	s_and_b64 vcc, exec, s[4:5]
	v_mov_b32_e32 v32, 1.0
	s_cbranch_vccnz .LBB0_639
	global_load_dword v32, v[6:7], off offset:96
.LBB0_639:
	v_or_b32_e32 v33, 24, v2
	v_mad_i64_i32 v[44:45], s[12:13], v33, s20, 0
	v_lshl_add_u64 v[44:45], v[44:45], 2, v[4:5]
	global_load_dword v33, v[44:45], off nt
	s_and_b64 vcc, exec, s[4:5]
	s_cbranch_vccnz .LBB0_641
	global_load_dword v31, v[6:7], off offset:104
.LBB0_641:
	v_or_b32_e32 v35, 26, v2
	v_mad_i64_i32 v[44:45], s[12:13], v35, s20, 0
	v_lshl_add_u64 v[44:45], v[44:45], 2, v[4:5]
	global_load_dword v35, v[44:45], off nt
	v_mov_b32_e32 v43, 1.0
	s_and_b64 vcc, exec, s[4:5]
	v_mov_b32_e32 v44, 1.0
	s_cbranch_vccnz .LBB0_643
	global_load_dword v44, v[6:7], off offset:112
.LBB0_643:
	v_or_b32_e32 v45, 28, v2
	v_mad_i64_i32 v[46:47], s[12:13], v45, s20, 0
	v_lshl_add_u64 v[46:47], v[46:47], 2, v[4:5]
	global_load_dword v45, v[46:47], off nt
	s_and_b64 vcc, exec, s[4:5]
	s_cbranch_vccnz .LBB0_645
	global_load_dword v43, v[6:7], off offset:120
.LBB0_645:
	v_or_b32_e32 v46, 30, v2
	v_mad_i64_i32 v[46:47], s[12:13], v46, s20, 0
	v_lshl_add_u64 v[46:47], v[46:47], 2, v[4:5]
	global_load_dword v46, v[46:47], off nt
	v_mov_b32_e32 v47, 1.0
	s_and_b64 vcc, exec, s[4:5]
	v_mov_b32_e32 v48, 1.0
	s_cbranch_vccnz .LBB0_647
	global_load_dword v48, v[6:7], off offset:128
.LBB0_647:
	v_or_b32_e32 v49, 32, v2
	v_mad_i64_i32 v[50:51], s[12:13], v49, s20, 0
	v_lshl_add_u64 v[50:51], v[50:51], 2, v[4:5]
	global_load_dword v49, v[50:51], off nt
	s_and_b64 vcc, exec, s[4:5]
	s_cbranch_vccnz .LBB0_649
	global_load_dword v47, v[6:7], off offset:136
.LBB0_649:
	v_or_b32_e32 v50, 34, v2
	v_mad_i64_i32 v[50:51], s[12:13], v50, s20, 0
	v_lshl_add_u64 v[50:51], v[50:51], 2, v[4:5]
	global_load_dword v50, v[50:51], off nt
	v_mov_b32_e32 v51, 1.0
	s_and_b64 vcc, exec, s[4:5]
	v_mov_b32_e32 v52, 1.0
	s_cbranch_vccnz .LBB0_651
	global_load_dword v52, v[6:7], off offset:144
.LBB0_651:
	v_or_b32_e32 v53, 36, v2
	v_mad_i64_i32 v[54:55], s[12:13], v53, s20, 0
	v_lshl_add_u64 v[54:55], v[54:55], 2, v[4:5]
	global_load_dword v53, v[54:55], off nt
	s_and_b64 vcc, exec, s[4:5]
	s_cbranch_vccnz .LBB0_653
	global_load_dword v51, v[6:7], off offset:152
.LBB0_653:
	v_or_b32_e32 v54, 38, v2
	v_mad_i64_i32 v[54:55], s[12:13], v54, s20, 0
	v_lshl_add_u64 v[54:55], v[54:55], 2, v[4:5]
	global_load_dword v54, v[54:55], off nt
	v_mov_b32_e32 v55, 1.0
	s_and_b64 vcc, exec, s[4:5]
	v_mov_b32_e32 v56, 1.0
	s_cbranch_vccnz .LBB0_655
	global_load_dword v56, v[6:7], off offset:160
.LBB0_655:
	v_or_b32_e32 v57, 40, v2
	v_mad_i64_i32 v[58:59], s[12:13], v57, s20, 0
	v_lshl_add_u64 v[58:59], v[58:59], 2, v[4:5]
	global_load_dword v57, v[58:59], off nt
	s_and_b64 vcc, exec, s[4:5]
	s_cbranch_vccnz .LBB0_657
	global_load_dword v55, v[6:7], off offset:168
.LBB0_657:
	v_or_b32_e32 v58, 42, v2
	v_mad_i64_i32 v[58:59], s[12:13], v58, s20, 0
	v_lshl_add_u64 v[58:59], v[58:59], 2, v[4:5]
	global_load_dword v58, v[58:59], off nt
	v_mov_b32_e32 v59, 1.0
	s_and_b64 vcc, exec, s[4:5]
	v_mov_b32_e32 v60, 1.0
	s_cbranch_vccnz .LBB0_659
	global_load_dword v60, v[6:7], off offset:176
.LBB0_659:
	v_or_b32_e32 v61, 44, v2
	v_mad_i64_i32 v[62:63], s[12:13], v61, s20, 0
	v_lshl_add_u64 v[62:63], v[62:63], 2, v[4:5]
	global_load_dword v61, v[62:63], off nt
	s_and_b64 vcc, exec, s[4:5]
	s_cbranch_vccnz .LBB0_661
	global_load_dword v59, v[6:7], off offset:184
.LBB0_661:
	v_or_b32_e32 v62, 46, v2
	v_mad_i64_i32 v[62:63], s[12:13], v62, s20, 0
	v_lshl_add_u64 v[62:63], v[62:63], 2, v[4:5]
	global_load_dword v62, v[62:63], off nt
	v_mov_b32_e32 v63, 1.0
	s_and_b64 vcc, exec, s[4:5]
	v_mov_b32_e32 v64, 1.0
	s_cbranch_vccnz .LBB0_663
	global_load_dword v64, v[6:7], off offset:192
.LBB0_663:
	v_or_b32_e32 v65, 48, v2
	v_mad_i64_i32 v[66:67], s[12:13], v65, s20, 0
	v_lshl_add_u64 v[66:67], v[66:67], 2, v[4:5]
	global_load_dword v65, v[66:67], off nt
	s_and_b64 vcc, exec, s[4:5]
	s_cbranch_vccnz .LBB0_665
	global_load_dword v63, v[6:7], off offset:200
.LBB0_665:
	v_or_b32_e32 v66, 50, v2
	v_mad_i64_i32 v[66:67], s[12:13], v66, s20, 0
	v_lshl_add_u64 v[66:67], v[66:67], 2, v[4:5]
	global_load_dword v66, v[66:67], off nt
	v_mov_b32_e32 v67, 1.0
	s_and_b64 vcc, exec, s[4:5]
	v_mov_b32_e32 v68, 1.0
	s_cbranch_vccnz .LBB0_667
	global_load_dword v68, v[6:7], off offset:208
.LBB0_667:
	v_or_b32_e32 v69, 52, v2
	v_mad_i64_i32 v[70:71], s[12:13], v69, s20, 0
	v_lshl_add_u64 v[70:71], v[70:71], 2, v[4:5]
	global_load_dword v69, v[70:71], off nt
	s_and_b64 vcc, exec, s[4:5]
	s_cbranch_vccnz .LBB0_669
	global_load_dword v67, v[6:7], off offset:216
.LBB0_669:
	v_or_b32_e32 v70, 54, v2
	v_mad_i64_i32 v[70:71], s[12:13], v70, s20, 0
	v_lshl_add_u64 v[70:71], v[70:71], 2, v[4:5]
	global_load_dword v70, v[70:71], off nt
	v_mov_b32_e32 v71, 1.0
	s_and_b64 vcc, exec, s[4:5]
	v_mov_b32_e32 v72, 1.0
	s_cbranch_vccnz .LBB0_671
	global_load_dword v72, v[6:7], off offset:224
.LBB0_671:
	v_or_b32_e32 v73, 56, v2
	v_mad_i64_i32 v[74:75], s[12:13], v73, s20, 0
	v_lshl_add_u64 v[74:75], v[74:75], 2, v[4:5]
	global_load_dword v73, v[74:75], off nt
	s_and_b64 vcc, exec, s[4:5]
	s_cbranch_vccnz .LBB0_673
	global_load_dword v71, v[6:7], off offset:232
.LBB0_673:
	v_or_b32_e32 v74, 58, v2
	v_mad_i64_i32 v[74:75], s[12:13], v74, s20, 0
	v_lshl_add_u64 v[74:75], v[74:75], 2, v[4:5]
	global_load_dword v75, v[74:75], off nt
	v_mov_b32_e32 v74, 1.0
	s_and_b64 vcc, exec, s[4:5]
	v_mov_b32_e32 v76, 1.0
	s_cbranch_vccnz .LBB0_675
	global_load_dword v76, v[6:7], off offset:240
.LBB0_675:
	v_or_b32_e32 v77, 60, v2
	v_mad_i64_i32 v[78:79], s[12:13], v77, s20, 0
	v_lshl_add_u64 v[78:79], v[78:79], 2, v[4:5]
	global_load_dword v77, v[78:79], off nt
	s_and_b64 vcc, exec, s[4:5]
	s_cbranch_vccnz .LBB0_677
	global_load_dword v74, v[6:7], off offset:248
